# v17 + first K-iteration peeled in 6 GEMM loops (first-touch MFMAs use C=0, accumulator zeroing removed), run 1
# speedup vs baseline: 1.0106x; 1.0106x over previous
; template <class Epi, bool ALIGN_EPI, bool SPLITA>
; __device__ __forceinline__ void gemm_phase(LAS unsigned char* lds, const Gemm g, const StaticOrder& S, const Epi& E) {
;     ...
;         const bool has_next = S.next(ui + 1, nxt);
;         const char* nA = has_next ? baseA1(nxt) : cA;
;         const char* nB = has_next ? baseB(nxt) : cB;
;         const bool mirN = has_next ? mirrored(nxt) : mirC;
;         for (int t = 0; t < nt; t += 2) {
;             const bool last = (t == nt - 2);
;             if constexpr (Epi::MIDK) { if (t == g.ksplit) E.mid(acc, cur, wr, wc, fr, fq); }
;             const char *a1, *a2;
;             if constexpr (SPLITA) {
;                 a1 = (t + 1 < g.ksplit) ? cA + (size_t)(t + 1) * kstep : cA2 + (size_t)(t + 1 - g.ksplit) * 2048;
;                 a2 = last ? nA : ((t + 2 < g.ksplit) ? cA + (size_t)(t + 2) * kstep : cA2 + (size_t)(t + 2 - g.ksplit) * 2048);
;             } else { a1 = cA + kofs(t + 1); a2 = last ? nA : cA + kofs(t + 2); }
;             const char* b2 = last ? nB : cB + (size_t)(t + 2) * kstepB;
;             const bool s2a = SPLITA && (t + 1 >= g.ksplit), s2b = SPLITA && !last && (t + 2 >= g.ksplit);
;             const char* a3 = a2 + ((Epi::KSUB || s2b) ? (size_t)2048 : kstep); const char* b3 = b2 + kstepB;
;             const bool m1 = SPLITA && mirC && (t + 1 < g.ksplit), m2 = SPLITA && (last ? mirN : (mirC && (t + 2 < g.ksplit)));
;             const unsigned vo1[2] = {s2a ? voffA2[0] : m1 ? voffAm[0] : voffA[0], s2a ? voffA2[1] : m1 ? voffAm[1] : voffA[1]}, vo2[2] = {s2b ? voffA2[0] : m2 ? voffAm[0] : voffA[0], s2b ? voffA2[1] : m2 ? voffAm[1] : voffA[1]};
;             const char* a1h = m1 ? a1 - hstepA : a1 + hstepA; const char* a2h = m2 ? a2 - hstepA : a2 + hstepA;
;             PG8_LDB(B0, 0, 0); PG8_LDB(B1, 0, 1); PG8_SCHED; PG8_LDA(At, 0, 0); PG8_STAGE(PG8_SA(1, 1), a1h, vo1);
;             PG8_WAIT_V(8); PG8_WAIT_L(0); PG8_BAR; PG8_MMA(0, 0, At, B0); PG8_MMA(0, 1, At, B1); PG8_BAR; PG8_SCHED;
;             PG8_LDA(At, 0, 1); PG8_STAGE(PG8_SB(0, 0), b2, voffB); PG8_STAGE(PG8_SB(0, 1), b2 + hstepB, voffB); PG8_STAGE(PG8_SA(0, 0), a2, vo2);
;             PG8_WAIT_V(8); PG8_WAIT_L(0); PG8_BAR; PG8_MMA(1, 0, At, B0); PG8_MMA(1, 1, At, B1); PG8_BAR; PG8_SCHED;
;             PG8_LDB(B0, 1, 0); PG8_LDB(B1, 1, 1); PG8_SCHED; PG8_LDA(At, 1, 0); PG8_STAGE(PG8_SA(0, 1), a2h, vo2);
.LBB0_228:
	s_ashr_i32 s27, s26, 31
	s_lshl_b64 s[38:39], s[26:27], 19
	s_add_u32 s38, s34, s38
	s_addc_u32 s39, s35, s39
	s_and_b64 s[40:41], s[2:3], exec
	s_cselect_b32 s27, s39, s43
	s_cselect_b32 s33, s38, s42
	s_ashr_i32 s29, s28, 31
	s_lshl_b64 s[40:41], s[28:29], 19
	s_add_u32 s40, s72, s40
	s_addc_u32 s41, s73, s41
	s_and_b64 s[46:47], s[2:3], exec
	s_cselect_b32 s29, s41, s45
	s_cselect_b32 s60, s40, s44
	s_add_u32 s42, s42, 0x40080
	s_addc_u32 s43, s43, 0
	s_add_u32 s61, s44, 0x100
	s_addc_u32 vcc_lo, s45, 0
	s_mov_b32 vcc_hi, -2
	ds_read_b128 v[130:133], v191
	ds_read_b128 v[134:137], v191 offset:1024
	ds_read_b128 v[138:141], v191 offset:2048
	ds_read_b128 v[142:145], v191 offset:3072
	ds_read_b128 v[146:149], v192
	ds_read_b128 v[150:153], v192 offset:1024
	ds_read_b128 v[154:157], v192 offset:2048
	ds_read_b128 v[158:161], v192 offset:3072
	s_add_u32 s0, s42, 0xfffc0080
	s_addc_u32 s1, s43, -1
	s_cmp_eq_u32 vcc_hi, 12
	s_cselect_b32 s47, s27, s1
	s_cselect_b32 s46, s33, s0
	s_cselect_b32 s45, s29, vcc_lo
	s_cselect_b32 s44, s60, s61
	s_add_i32 m0, s87, 0xc000
	ds_read_b128 v[198:201], v193
	ds_read_b128 v[202:205], v193 offset:1024
	ds_read_b128 v[206:209], v193 offset:2048
	ds_read_b128 v[210:213], v193 offset:3072
	ds_read_b128 v[214:217], v193 offset:4096
	ds_read_b128 v[218:221], v193 offset:5120
	ds_read_b128 v[222:225], v193 offset:6144
	ds_read_b128 v[226:229], v193 offset:7168
	global_load_lds_dwordx4 v182, s[42:43]
	s_add_i32 m0, s87, 0xe000
	s_nop 0
	global_load_lds_dwordx4 v184, s[42:43]
	s_waitcnt vmcnt(8)
	s_waitcnt lgkmcnt(0)
	s_barrier
	s_setprio 1
	s_waitcnt lgkmcnt(0)
	v_mfma_f32_16x16x32_bf16 v[126:129], v[130:133], v[198:201], 0
	v_mfma_f32_16x16x32_bf16 v[122:125], v[138:141], v[198:201], 0
	v_mfma_f32_16x16x32_bf16 v[110:113], v[130:133], v[206:209], 0
	v_mfma_f32_16x16x32_bf16 v[106:109], v[138:141], v[206:209], 0
	v_mfma_f32_16x16x32_bf16 v[94:97], v[130:133], v[214:217], 0
	v_mfma_f32_16x16x32_bf16 v[90:93], v[138:141], v[214:217], 0
	v_mfma_f32_16x16x32_bf16 v[78:81], v[130:133], v[222:225], 0
	v_mfma_f32_16x16x32_bf16 v[74:77], v[138:141], v[222:225], 0
	v_mfma_f32_16x16x32_bf16 v[126:129], v[134:137], v[202:205], v[126:129]
	v_mfma_f32_16x16x32_bf16 v[122:125], v[142:145], v[202:205], v[122:125]
	v_mfma_f32_16x16x32_bf16 v[110:113], v[134:137], v[210:213], v[110:113]
	v_mfma_f32_16x16x32_bf16 v[106:109], v[142:145], v[210:213], v[106:109]
	v_mfma_f32_16x16x32_bf16 v[94:97], v[134:137], v[218:221], v[94:97]
	v_mfma_f32_16x16x32_bf16 v[90:93], v[142:145], v[218:221], v[90:93]
	v_mfma_f32_16x16x32_bf16 v[78:81], v[134:137], v[226:229], v[78:81]
	v_mfma_f32_16x16x32_bf16 v[74:77], v[142:145], v[226:229], v[74:77]
	s_setprio 0
	s_setprio 1
	v_mfma_f32_16x16x32_bf16 v[118:121], v[146:149], v[198:201], 0
	v_mfma_f32_16x16x32_bf16 v[114:117], v[154:157], v[198:201], 0
	v_mfma_f32_16x16x32_bf16 v[102:105], v[146:149], v[206:209], 0
	v_mfma_f32_16x16x32_bf16 v[98:101], v[154:157], v[206:209], 0
	v_mfma_f32_16x16x32_bf16 v[86:89], v[146:149], v[214:217], 0
	v_mfma_f32_16x16x32_bf16 v[82:85], v[154:157], v[214:217], 0
	v_mfma_f32_16x16x32_bf16 v[70:73], v[146:149], v[222:225], 0
	v_mfma_f32_16x16x32_bf16 v[66:69], v[154:157], v[222:225], 0
	v_mfma_f32_16x16x32_bf16 v[118:121], v[150:153], v[202:205], v[118:121]
	v_mfma_f32_16x16x32_bf16 v[114:117], v[158:161], v[202:205], v[114:117]
	v_mfma_f32_16x16x32_bf16 v[102:105], v[150:153], v[210:213], v[102:105]
	v_mfma_f32_16x16x32_bf16 v[98:101], v[158:161], v[210:213], v[98:101]
	v_mfma_f32_16x16x32_bf16 v[86:89], v[150:153], v[218:221], v[86:89]
	v_mfma_f32_16x16x32_bf16 v[82:85], v[158:161], v[218:221], v[82:85]
	v_mfma_f32_16x16x32_bf16 v[70:73], v[150:153], v[226:229], v[70:73]
	v_mfma_f32_16x16x32_bf16 v[66:69], v[158:161], v[226:229], v[66:69]
	s_setprio 0
	s_barrier
	s_add_u32 s98, s44, s8
	s_addc_u32 s99, s45, s9
	s_add_u32 s100, s46, s8
	s_addc_u32 s101, s47, s9
	s_add_i32 s0, s97, s80
	s_mov_b32 m0, s0
	ds_read_b128 v[198:201], v193 offset:16384
	ds_read_b128 v[202:205], v193 offset:17408
	ds_read_b128 v[206:209], v193 offset:18432
	ds_read_b128 v[210:213], v193 offset:19456
	ds_read_b128 v[214:217], v193 offset:20480
	ds_read_b128 v[218:221], v193 offset:21504
	ds_read_b128 v[222:225], v193 offset:22528
	ds_read_b128 v[226:229], v193 offset:23552
	global_load_lds_dwordx4 v168, s[44:45]
	s_add_i32 m0, s0, 0x2000
	s_add_u32 s0, s44, 0x40000
	s_addc_u32 s1, s45, 0
	s_add_i32 s78, s64, s80
	global_load_lds_dwordx4 v164, s[44:45]
	s_mov_b32 m0, s78
	s_nop 0
	global_load_lds_dwordx4 v168, s[0:1]
	s_add_i32 m0, s78, 0x2000
	s_nop 0
	global_load_lds_dwordx4 v164, s[0:1]
	s_mov_b32 m0, s87
	s_nop 0
	global_load_lds_dwordx4 v170, s[46:47]
	s_mov_b32 m0, s88
	s_nop 0
	global_load_lds_dwordx4 v166, s[46:47]
	s_waitcnt vmcnt(8)
	s_waitcnt lgkmcnt(0)
	s_barrier
; #define PG8_STAGE(bufoff, gbase, voff) do { _Pragma("unroll") for (int _i = 0; _i < 2; ++_i) \
;         __builtin_amdgcn_global_load_lds((const unsigned*)((const char*)(gbase) + (voff)[_i]), (LAS unsigned*)(lds + (bufoff) + ldsw + _i * 8192), 16, 0, 0); } while (0)
; #define PG8_LDA(dst, b, h) do { _Pragma("unroll") for (int m = 0; m < 4; ++m) _Pragma("unroll") for (int k = 0; k < 2; ++k) dst[m][k] = *(const LAS bf16x8*)(lds + PG8_SA(b, h) + aoff + m * 2048 + k * 1024); } while (0)
; #define PG8_LDB(dst, b, h) do { _Pragma("unroll") for (int n = 0; n < 2; ++n) _Pragma("unroll") for (int k = 0; k < 2; ++k) dst[n][k] = *(const LAS bf16x8*)(lds + PG8_SB(b, h) + boff + n * 2048 + k * 1024); } while (0)
; #define PG8_MMA(ai, bj, At, Bt) do { __builtin_amdgcn_s_setprio(1); _Pragma("unroll") for (int m = 0; m < 4; ++m) _Pragma("unroll") for (int n = 0; n < 2; ++n) _Pragma("unroll") for (int k = 0; k < 2; ++k) \
;         acc[ai][bj][m][n] = __builtin_amdgcn_mfma_f32_16x16x32_bf16(Bt[n][k], At[m][k], acc[ai][bj][m][n], 0, 0, 0); __builtin_amdgcn_s_setprio(0); } while (0)
; #define PG8_WAIT_V(n) asm volatile("s_waitcnt vmcnt(" #n ")" ::: "memory")
; #define PG8_WAIT_L(n) asm volatile("s_waitcnt lgkmcnt(" #n ")" ::: "memory")
; #define PG8_BAR __builtin_amdgcn_s_barrier()
; #define PG8_SCHED __builtin_amdgcn_sched_barrier(0)
; template <class Epi, bool ALIGN_EPI, bool SPLITA>
; __device__ __forceinline__ void gemm_phase(LAS unsigned char* lds, const Gemm g, const StaticOrder& S, const Epi& E) {
;     ...
;             PG8_WAIT_V(8); PG8_WAIT_L(0); PG8_BAR; PG8_MMA(0, 0, At, B0); PG8_MMA(0, 1, At, B1); PG8_BAR; PG8_SCHED;
;             PG8_LDA(At, 0, 1); PG8_STAGE(PG8_SB(0, 0), b2, voffB); PG8_STAGE(PG8_SB(0, 1), b2 + hstepB, voffB); PG8_STAGE(PG8_SA(0, 0), a2, vo2);
;             PG8_WAIT_V(8); PG8_WAIT_L(0); PG8_BAR; PG8_MMA(1, 0, At, B0); PG8_MMA(1, 1, At, B1); PG8_BAR; PG8_SCHED;
;             PG8_LDB(B0, 1, 0); PG8_LDB(B1, 1, 1); PG8_SCHED; PG8_LDA(At, 1, 0); PG8_STAGE(PG8_SA(0, 1), a2h, vo2);
;             PG8_WAIT_V(8); PG8_WAIT_L(0); PG8_BAR; PG8_MMA(0, 0, At, B0); PG8_MMA(0, 1, At, B1); PG8_BAR; PG8_SCHED;
	s_setprio 1
	s_waitcnt lgkmcnt(0)
	v_mfma_f32_16x16x32_bf16 v[62:65], v[130:133], v[198:201], 0
	v_mfma_f32_16x16x32_bf16 v[58:61], v[138:141], v[198:201], 0
	v_mfma_f32_16x16x32_bf16 v[38:41], v[130:133], v[206:209], 0
	v_mfma_f32_16x16x32_bf16 v[34:37], v[138:141], v[206:209], 0
	v_mfma_f32_16x16x32_bf16 v[22:25], v[130:133], v[214:217], 0
	v_mfma_f32_16x16x32_bf16 v[18:21], v[138:141], v[214:217], 0
	v_mfma_f32_16x16x32_bf16 v[6:9], v[130:133], v[222:225], 0
	v_mfma_f32_16x16x32_bf16 v[2:5], v[138:141], v[222:225], 0
	v_mfma_f32_16x16x32_bf16 v[62:65], v[134:137], v[202:205], v[62:65]
	v_mfma_f32_16x16x32_bf16 v[58:61], v[142:145], v[202:205], v[58:61]
	v_mfma_f32_16x16x32_bf16 v[38:41], v[134:137], v[210:213], v[38:41]
	v_mfma_f32_16x16x32_bf16 v[34:37], v[142:145], v[210:213], v[34:37]
	v_mfma_f32_16x16x32_bf16 v[22:25], v[134:137], v[218:221], v[22:25]
	v_mfma_f32_16x16x32_bf16 v[18:21], v[142:145], v[218:221], v[18:21]
	v_mfma_f32_16x16x32_bf16 v[6:9], v[134:137], v[226:229], v[6:9]
	v_mfma_f32_16x16x32_bf16 v[2:5], v[142:145], v[226:229], v[2:5]
	s_setprio 0
	s_setprio 1
	v_mfma_f32_16x16x32_bf16 v[54:57], v[146:149], v[198:201], 0
	v_mfma_f32_16x16x32_bf16 v[50:53], v[154:157], v[198:201], 0
	v_mfma_f32_16x16x32_bf16 v[42:45], v[146:149], v[206:209], 0
	v_mfma_f32_16x16x32_bf16 v[46:49], v[154:157], v[206:209], 0
	v_mfma_f32_16x16x32_bf16 v[26:29], v[146:149], v[214:217], 0
	v_mfma_f32_16x16x32_bf16 v[30:33], v[154:157], v[214:217], 0
	v_mfma_f32_16x16x32_bf16 v[10:13], v[146:149], v[222:225], 0
	v_mfma_f32_16x16x32_bf16 v[14:17], v[154:157], v[222:225], 0
	v_mfma_f32_16x16x32_bf16 v[54:57], v[150:153], v[202:205], v[54:57]
	v_mfma_f32_16x16x32_bf16 v[50:53], v[158:161], v[202:205], v[50:53]
	v_mfma_f32_16x16x32_bf16 v[42:45], v[150:153], v[210:213], v[42:45]
	v_mfma_f32_16x16x32_bf16 v[46:49], v[158:161], v[210:213], v[46:49]
	v_mfma_f32_16x16x32_bf16 v[26:29], v[150:153], v[218:221], v[26:29]
	v_mfma_f32_16x16x32_bf16 v[30:33], v[158:161], v[218:221], v[30:33]
	v_mfma_f32_16x16x32_bf16 v[10:13], v[150:153], v[226:229], v[10:13]
	v_mfma_f32_16x16x32_bf16 v[14:17], v[158:161], v[226:229], v[14:17]
	s_setprio 0
	s_barrier
	s_add_i32 s78, 0, 0x18000
	s_add_i32 s89, 0, 0x1c000
	v_add_u32_e32 v142, s78, v163
	v_add_u32_e32 v158, s89, v163
	ds_read_b128 v[130:133], v142
	ds_read_b128 v[134:137], v142 offset:1024
	ds_read_b128 v[138:141], v142 offset:2048
	ds_read_b128 v[142:145], v142 offset:3072
	ds_read_b128 v[146:149], v158
	ds_read_b128 v[150:153], v158 offset:1024
	ds_read_b128 v[154:157], v158 offset:2048
	ds_read_b128 v[158:161], v158 offset:3072
	s_add_u32 s0, s46, 0x40000
	s_addc_u32 s1, s47, 0
	s_mov_b32 m0, s90
	ds_read_b128 v[198:201], v193 offset:32768
	ds_read_b128 v[202:205], v193 offset:33792
	ds_read_b128 v[206:209], v193 offset:34816
	ds_read_b128 v[210:213], v193 offset:35840
	ds_read_b128 v[214:217], v193 offset:36864
	ds_read_b128 v[218:221], v193 offset:37888
	ds_read_b128 v[222:225], v193 offset:38912
	ds_read_b128 v[226:229], v193 offset:39936
	global_load_lds_dwordx4 v170, s[0:1]
	s_mov_b32 m0, s91
	s_nop 0
	global_load_lds_dwordx4 v166, s[0:1]
	s_waitcnt vmcnt(8)
	s_waitcnt lgkmcnt(0)
	s_barrier
	s_setprio 1
	s_waitcnt lgkmcnt(0)
	v_mfma_f32_16x16x32_bf16 v[126:129], v[130:133], v[198:201], v[126:129]
	v_mfma_f32_16x16x32_bf16 v[122:125], v[138:141], v[198:201], v[122:125]
	v_mfma_f32_16x16x32_bf16 v[110:113], v[130:133], v[206:209], v[110:113]
	v_mfma_f32_16x16x32_bf16 v[106:109], v[138:141], v[206:209], v[106:109]
	v_mfma_f32_16x16x32_bf16 v[94:97], v[130:133], v[214:217], v[94:97]
	v_mfma_f32_16x16x32_bf16 v[90:93], v[138:141], v[214:217], v[90:93]
	v_mfma_f32_16x16x32_bf16 v[78:81], v[130:133], v[222:225], v[78:81]
	v_mfma_f32_16x16x32_bf16 v[74:77], v[138:141], v[222:225], v[74:77]
	v_mfma_f32_16x16x32_bf16 v[126:129], v[134:137], v[202:205], v[126:129]
	v_mfma_f32_16x16x32_bf16 v[122:125], v[142:145], v[202:205], v[122:125]
	v_mfma_f32_16x16x32_bf16 v[110:113], v[134:137], v[210:213], v[110:113]
	v_mfma_f32_16x16x32_bf16 v[106:109], v[142:145], v[210:213], v[106:109]
	v_mfma_f32_16x16x32_bf16 v[94:97], v[134:137], v[218:221], v[94:97]
	v_mfma_f32_16x16x32_bf16 v[90:93], v[142:145], v[218:221], v[90:93]
	v_mfma_f32_16x16x32_bf16 v[78:81], v[134:137], v[226:229], v[78:81]
	v_mfma_f32_16x16x32_bf16 v[74:77], v[142:145], v[226:229], v[74:77]
	s_setprio 0
	s_setprio 1
	v_mfma_f32_16x16x32_bf16 v[118:121], v[146:149], v[198:201], v[118:121]
	v_mfma_f32_16x16x32_bf16 v[114:117], v[154:157], v[198:201], v[114:117]
	v_mfma_f32_16x16x32_bf16 v[102:105], v[146:149], v[206:209], v[102:105]
	v_mfma_f32_16x16x32_bf16 v[98:101], v[154:157], v[206:209], v[98:101]
	v_mfma_f32_16x16x32_bf16 v[86:89], v[146:149], v[214:217], v[86:89]
	v_mfma_f32_16x16x32_bf16 v[82:85], v[154:157], v[214:217], v[82:85]
	v_mfma_f32_16x16x32_bf16 v[70:73], v[146:149], v[222:225], v[70:73]
	v_mfma_f32_16x16x32_bf16 v[66:69], v[154:157], v[222:225], v[66:69]
	v_mfma_f32_16x16x32_bf16 v[118:121], v[150:153], v[202:205], v[118:121]
	v_mfma_f32_16x16x32_bf16 v[114:117], v[158:161], v[202:205], v[114:117]
	v_mfma_f32_16x16x32_bf16 v[102:105], v[150:153], v[210:213], v[102:105]
	v_mfma_f32_16x16x32_bf16 v[98:101], v[158:161], v[210:213], v[98:101]
	v_mfma_f32_16x16x32_bf16 v[86:89], v[150:153], v[218:221], v[86:89]
	v_mfma_f32_16x16x32_bf16 v[82:85], v[158:161], v[218:221], v[82:85]
	v_mfma_f32_16x16x32_bf16 v[70:73], v[150:153], v[226:229], v[70:73]
	v_mfma_f32_16x16x32_bf16 v[66:69], v[158:161], v[226:229], v[66:69]
	s_setprio 0
	s_barrier
; #define PG8_STAGE(bufoff, gbase, voff) do { _Pragma("unroll") for (int _i = 0; _i < 2; ++_i) \
;         __builtin_amdgcn_global_load_lds((const unsigned*)((const char*)(gbase) + (voff)[_i]), (LAS unsigned*)(lds + (bufoff) + ldsw + _i * 8192), 16, 0, 0); } while (0)
; #define PG8_LDA(dst, b, h) do { _Pragma("unroll") for (int m = 0; m < 4; ++m) _Pragma("unroll") for (int k = 0; k < 2; ++k) dst[m][k] = *(const LAS bf16x8*)(lds + PG8_SA(b, h) + aoff + m * 2048 + k * 1024); } while (0)
; #define PG8_MMA(ai, bj, At, Bt) do { __builtin_amdgcn_s_setprio(1); _Pragma("unroll") for (int m = 0; m < 4; ++m) _Pragma("unroll") for (int n = 0; n < 2; ++n) _Pragma("unroll") for (int k = 0; k < 2; ++k) \
;         acc[ai][bj][m][n] = __builtin_amdgcn_mfma_f32_16x16x32_bf16(Bt[n][k], At[m][k], acc[ai][bj][m][n], 0, 0, 0); __builtin_amdgcn_s_setprio(0); } while (0)
; #define PG8_WAIT_V(n) asm volatile("s_waitcnt vmcnt(" #n ")" ::: "memory")
; #define PG8_WAIT_L(n) asm volatile("s_waitcnt lgkmcnt(" #n ")" ::: "memory")
; #define PG8_BAR __builtin_amdgcn_s_barrier()
; #define PG8_SCHED __builtin_amdgcn_sched_barrier(0)
; template <class Epi, bool ALIGN_EPI, bool SPLITA>
; __device__ __forceinline__ void gemm_phase(LAS unsigned char* lds, const Gemm g, const StaticOrder& S, const Epi& E) {
;     ...
;             PG8_LDA(At, 1, 1); PG8_STAGE(PG8_SB(1, 0), b3, voffB); PG8_STAGE(PG8_SB(1, 1), b3 + hstepB, voffB); PG8_STAGE(PG8_SA(1, 0), a3, vo2);
;             PG8_WAIT_V(8); PG8_WAIT_L(0); PG8_BAR; PG8_MMA(1, 0, At, B0); PG8_MMA(1, 1, At, B1); PG8_BAR; PG8_SCHED;
	s_add_i32 s0, s78, s80
	s_mov_b32 m0, s0
	ds_read_b128 v[198:201], v193 offset:49152
	ds_read_b128 v[202:205], v193 offset:50176
	ds_read_b128 v[206:209], v193 offset:51200
	ds_read_b128 v[210:213], v193 offset:52224
	ds_read_b128 v[214:217], v193 offset:53248
	ds_read_b128 v[218:221], v193 offset:54272
	ds_read_b128 v[222:225], v193 offset:55296
	ds_read_b128 v[226:229], v193 offset:56320
	global_load_lds_dwordx4 v168, s[98:99]
	s_add_i32 m0, s0, 0x2000
	s_add_u32 s0, s44, 0x40080
	s_addc_u32 s1, s45, 0
	s_add_i32 s44, s89, s80
	global_load_lds_dwordx4 v164, s[98:99]
	s_mov_b32 m0, s44
	s_nop 0
	global_load_lds_dwordx4 v168, s[0:1]
	s_add_i32 m0, s44, 0x2000
	s_nop 0
	global_load_lds_dwordx4 v164, s[0:1]
	s_mov_b32 m0, s94
	s_nop 0
	global_load_lds_dwordx4 v170, s[100:101]
	s_mov_b32 m0, s95
	s_nop 0
	global_load_lds_dwordx4 v166, s[100:101]
	s_waitcnt vmcnt(8)
	s_waitcnt lgkmcnt(0)
	s_barrier
	s_setprio 1
	s_waitcnt lgkmcnt(0)
	v_mfma_f32_16x16x32_bf16 v[62:65], v[130:133], v[198:201], v[62:65]
	v_mfma_f32_16x16x32_bf16 v[58:61], v[138:141], v[198:201], v[58:61]
	v_mfma_f32_16x16x32_bf16 v[38:41], v[130:133], v[206:209], v[38:41]
	v_mfma_f32_16x16x32_bf16 v[34:37], v[138:141], v[206:209], v[34:37]
	v_mfma_f32_16x16x32_bf16 v[22:25], v[130:133], v[214:217], v[22:25]
	v_mfma_f32_16x16x32_bf16 v[18:21], v[138:141], v[214:217], v[18:21]
	v_mfma_f32_16x16x32_bf16 v[6:9], v[130:133], v[222:225], v[6:9]
	v_mfma_f32_16x16x32_bf16 v[2:5], v[138:141], v[222:225], v[2:5]
	v_mfma_f32_16x16x32_bf16 v[62:65], v[134:137], v[202:205], v[62:65]
	v_mfma_f32_16x16x32_bf16 v[58:61], v[142:145], v[202:205], v[58:61]
	v_mfma_f32_16x16x32_bf16 v[38:41], v[134:137], v[210:213], v[38:41]
	v_mfma_f32_16x16x32_bf16 v[34:37], v[142:145], v[210:213], v[34:37]
	v_mfma_f32_16x16x32_bf16 v[22:25], v[134:137], v[218:221], v[22:25]
	v_mfma_f32_16x16x32_bf16 v[18:21], v[142:145], v[218:221], v[18:21]
	v_mfma_f32_16x16x32_bf16 v[6:9], v[134:137], v[226:229], v[6:9]
	v_mfma_f32_16x16x32_bf16 v[2:5], v[142:145], v[226:229], v[2:5]
	s_setprio 0
	s_setprio 1
	v_mfma_f32_16x16x32_bf16 v[54:57], v[146:149], v[198:201], v[54:57]
	v_mfma_f32_16x16x32_bf16 v[50:53], v[154:157], v[198:201], v[50:53]
	v_mfma_f32_16x16x32_bf16 v[42:45], v[146:149], v[206:209], v[42:45]
	v_mfma_f32_16x16x32_bf16 v[46:49], v[154:157], v[206:209], v[46:49]
	v_mfma_f32_16x16x32_bf16 v[26:29], v[146:149], v[214:217], v[26:29]
	v_mfma_f32_16x16x32_bf16 v[30:33], v[154:157], v[214:217], v[30:33]
	v_mfma_f32_16x16x32_bf16 v[10:13], v[146:149], v[222:225], v[10:13]
	v_mfma_f32_16x16x32_bf16 v[14:17], v[154:157], v[222:225], v[14:17]
	v_mfma_f32_16x16x32_bf16 v[54:57], v[150:153], v[202:205], v[54:57]
	v_mfma_f32_16x16x32_bf16 v[50:53], v[158:161], v[202:205], v[50:53]
	v_mfma_f32_16x16x32_bf16 v[42:45], v[150:153], v[210:213], v[42:45]
	v_mfma_f32_16x16x32_bf16 v[46:49], v[158:161], v[210:213], v[46:49]
	v_mfma_f32_16x16x32_bf16 v[26:29], v[150:153], v[218:221], v[26:29]
	v_mfma_f32_16x16x32_bf16 v[30:33], v[158:161], v[218:221], v[30:33]
	v_mfma_f32_16x16x32_bf16 v[10:13], v[150:153], v[226:229], v[10:13]
	v_mfma_f32_16x16x32_bf16 v[14:17], v[158:161], v[226:229], v[14:17]
	s_setprio 0
	s_barrier
	s_add_i32 vcc_hi, vcc_hi, 2
	s_add_u32 s42, s42, 0x100
	s_addc_u32 s43, s43, 0
	s_add_u32 s61, s61, 0x100
	s_addc_u32 vcc_lo, vcc_lo, 0

; template <class Epi, bool ALIGN_EPI, bool SPLITA>
; __device__ __forceinline__ void gemm_phase(LAS unsigned char* lds, const Gemm g, const StaticOrder& S, const Epi& E) {
;     ...
;         const bool has_next = S.next(ui + 1, nxt);
;         const char* nA = has_next ? baseA1(nxt) : cA;
;         const char* nB = has_next ? baseB(nxt) : cB;
;         const bool mirN = has_next ? mirrored(nxt) : mirC;
;         for (int t = 0; t < nt; t += 2) {
;             const bool last = (t == nt - 2);
;             if constexpr (Epi::MIDK) { if (t == g.ksplit) E.mid(acc, cur, wr, wc, fr, fq); }
;             const char *a1, *a2;
;             if constexpr (SPLITA) {
;                 a1 = (t + 1 < g.ksplit) ? cA + (size_t)(t + 1) * kstep : cA2 + (size_t)(t + 1 - g.ksplit) * 2048;
;                 a2 = last ? nA : ((t + 2 < g.ksplit) ? cA + (size_t)(t + 2) * kstep : cA2 + (size_t)(t + 2 - g.ksplit) * 2048);
;             } else { a1 = cA + kofs(t + 1); a2 = last ? nA : cA + kofs(t + 2); }
;             const char* b2 = last ? nB : cB + (size_t)(t + 2) * kstepB;
;             const bool s2a = SPLITA && (t + 1 >= g.ksplit), s2b = SPLITA && !last && (t + 2 >= g.ksplit);
;             const char* a3 = a2 + ((Epi::KSUB || s2b) ? (size_t)2048 : kstep); const char* b3 = b2 + kstepB;
;             const bool m1 = SPLITA && mirC && (t + 1 < g.ksplit), m2 = SPLITA && (last ? mirN : (mirC && (t + 2 < g.ksplit)));
;             const unsigned vo1[2] = {s2a ? voffA2[0] : m1 ? voffAm[0] : voffA[0], s2a ? voffA2[1] : m1 ? voffAm[1] : voffA[1]}, vo2[2] = {s2b ? voffA2[0] : m2 ? voffAm[0] : voffA[0], s2b ? voffA2[1] : m2 ? voffAm[1] : voffA[1]};
;             const char* a1h = m1 ? a1 - hstepA : a1 + hstepA; const char* a2h = m2 ? a2 - hstepA : a2 + hstepA;
;             PG8_LDB(B0, 0, 0); PG8_LDB(B1, 0, 1); PG8_SCHED; PG8_LDA(At, 0, 0); PG8_STAGE(PG8_SA(1, 1), a1h, vo1);
;             PG8_WAIT_V(8); PG8_WAIT_L(0); PG8_BAR; PG8_MMA(0, 0, At, B0); PG8_MMA(0, 1, At, B1); PG8_BAR; PG8_SCHED;
;             PG8_LDA(At, 0, 1); PG8_STAGE(PG8_SB(0, 0), b2, voffB); PG8_STAGE(PG8_SB(0, 1), b2 + hstepB, voffB); PG8_STAGE(PG8_SA(0, 0), a2, vo2);
;             PG8_WAIT_V(8); PG8_WAIT_L(0); PG8_BAR; PG8_MMA(1, 0, At, B0); PG8_MMA(1, 1, At, B1); PG8_BAR; PG8_SCHED;
;             PG8_LDB(B0, 1, 0); PG8_LDB(B1, 1, 1); PG8_SCHED; PG8_LDA(At, 1, 0); PG8_STAGE(PG8_SA(0, 1), a2h, vo2);
.LBB0_264:
	s_ashr_i32 s29, s28, 31
	s_lshl_b64 s[40:41], s[28:29], 19
	s_add_u32 s40, s6, s40
	s_addc_u32 s41, s7, s41
	s_and_b64 s[0:1], s[0:1], exec
	s_cselect_b32 s13, s41, s47
	s_cselect_b32 s27, s40, s46
	s_add_u32 s0, s46, 0x40080
	s_addc_u32 s1, s47, 0
	s_add_u32 s29, s44, 0x100
	s_addc_u32 s90, s45, 0
	s_mov_b32 s91, -2
	ds_read_b128 v[146:149], v152
	ds_read_b128 v[156:159], v152 offset:1024
	ds_read_b128 v[164:167], v152 offset:2048
	ds_read_b128 v[168:171], v152 offset:3072
	ds_read_b128 v[172:175], v153
	ds_read_b128 v[176:179], v153 offset:1024
	ds_read_b128 v[180:183], v153 offset:2048
	ds_read_b128 v[184:187], v153 offset:3072
	s_add_u32 s44, s0, 0xfffc0080
	s_addc_u32 s45, s1, -1
	s_cmp_eq_u32 s91, 12
	s_cselect_b32 s47, s13, s45
	s_cselect_b32 s46, s27, s44
	s_cselect_b32 s45, s39, s90
	s_cselect_b32 s44, s38, s29
	s_add_i32 m0, s43, 0xc000
	ds_read_b128 v[188:191], v154
	ds_read_b128 v[192:195], v154 offset:1024
	ds_read_b128 v[196:199], v154 offset:2048
	ds_read_b128 v[200:203], v154 offset:3072
	ds_read_b128 v[204:207], v154 offset:4096
	ds_read_b128 v[208:211], v154 offset:5120
	ds_read_b128 v[212:215], v154 offset:6144
	ds_read_b128 v[216:219], v154 offset:7168
	global_load_lds_dwordx4 v138, s[0:1]
	s_add_i32 m0, s43, 0xe000
	s_nop 0
	global_load_lds_dwordx4 v140, s[0:1]
	s_waitcnt vmcnt(8)
	s_waitcnt lgkmcnt(0)
	s_barrier
	s_setprio 1
	s_waitcnt lgkmcnt(0)
	v_mfma_f32_16x16x32_bf16 v[126:129], v[146:149], v[188:191], 0
	v_mfma_f32_16x16x32_bf16 v[122:125], v[164:167], v[188:191], 0
	v_mfma_f32_16x16x32_bf16 v[110:113], v[146:149], v[196:199], 0
	v_mfma_f32_16x16x32_bf16 v[106:109], v[164:167], v[196:199], 0
	v_mfma_f32_16x16x32_bf16 v[94:97], v[146:149], v[204:207], 0
	v_mfma_f32_16x16x32_bf16 v[90:93], v[164:167], v[204:207], 0
	v_mfma_f32_16x16x32_bf16 v[78:81], v[146:149], v[212:215], 0
	v_mfma_f32_16x16x32_bf16 v[74:77], v[164:167], v[212:215], 0
	v_mfma_f32_16x16x32_bf16 v[126:129], v[156:159], v[192:195], v[126:129]
	v_mfma_f32_16x16x32_bf16 v[122:125], v[168:171], v[192:195], v[122:125]
	v_mfma_f32_16x16x32_bf16 v[110:113], v[156:159], v[200:203], v[110:113]
	v_mfma_f32_16x16x32_bf16 v[106:109], v[168:171], v[200:203], v[106:109]
	v_mfma_f32_16x16x32_bf16 v[94:97], v[156:159], v[208:211], v[94:97]
	v_mfma_f32_16x16x32_bf16 v[90:93], v[168:171], v[208:211], v[90:93]
	v_mfma_f32_16x16x32_bf16 v[78:81], v[156:159], v[216:219], v[78:81]
	v_mfma_f32_16x16x32_bf16 v[74:77], v[168:171], v[216:219], v[74:77]
	s_setprio 0
	s_setprio 1
	v_mfma_f32_16x16x32_bf16 v[118:121], v[172:175], v[188:191], 0
	v_mfma_f32_16x16x32_bf16 v[114:117], v[180:183], v[188:191], 0
	v_mfma_f32_16x16x32_bf16 v[102:105], v[172:175], v[196:199], 0
	v_mfma_f32_16x16x32_bf16 v[98:101], v[180:183], v[196:199], 0
	v_mfma_f32_16x16x32_bf16 v[86:89], v[172:175], v[204:207], 0
	v_mfma_f32_16x16x32_bf16 v[82:85], v[180:183], v[204:207], 0
	v_mfma_f32_16x16x32_bf16 v[70:73], v[172:175], v[212:215], 0
	v_mfma_f32_16x16x32_bf16 v[66:69], v[180:183], v[212:215], 0
	v_mfma_f32_16x16x32_bf16 v[118:121], v[176:179], v[192:195], v[118:121]
	v_mfma_f32_16x16x32_bf16 v[114:117], v[184:187], v[192:195], v[114:117]
	v_mfma_f32_16x16x32_bf16 v[102:105], v[176:179], v[200:203], v[102:105]
	v_mfma_f32_16x16x32_bf16 v[98:101], v[184:187], v[200:203], v[98:101]
	v_mfma_f32_16x16x32_bf16 v[86:89], v[176:179], v[208:211], v[86:89]
	v_mfma_f32_16x16x32_bf16 v[82:85], v[184:187], v[208:211], v[82:85]
	v_mfma_f32_16x16x32_bf16 v[70:73], v[176:179], v[216:219], v[70:73]
	v_mfma_f32_16x16x32_bf16 v[66:69], v[184:187], v[216:219], v[66:69]
	s_setprio 0
	s_barrier
	s_add_u32 s98, s44, s8
	s_addc_u32 s99, s45, s9
	s_add_u32 s100, s46, s8
	s_addc_u32 s101, s47, s9
	s_add_i32 s89, s79, s33
	s_mov_b32 m0, s89
	ds_read_b128 v[188:191], v154 offset:16384
	ds_read_b128 v[192:195], v154 offset:17408
	ds_read_b128 v[196:199], v154 offset:18432
	ds_read_b128 v[200:203], v154 offset:19456
	ds_read_b128 v[204:207], v154 offset:20480
	ds_read_b128 v[208:211], v154 offset:21504
	ds_read_b128 v[212:215], v154 offset:22528
	ds_read_b128 v[216:219], v154 offset:23552
	global_load_lds_dwordx4 v134, s[44:45]
	s_add_i32 m0, s89, 0x2000
	s_add_u32 s92, s44, 0x200000
	s_addc_u32 s93, s45, 0
	s_add_i32 s89, s80, s33
	global_load_lds_dwordx4 v130, s[44:45]
	s_mov_b32 m0, s89
	s_nop 0
	global_load_lds_dwordx4 v134, s[92:93]
	s_add_i32 m0, s89, 0x2000
	s_nop 0
	global_load_lds_dwordx4 v130, s[92:93]
	s_mov_b32 m0, s43
	s_nop 0
	global_load_lds_dwordx4 v136, s[46:47]
	s_mov_b32 m0, s60
	s_nop 0
	global_load_lds_dwordx4 v132, s[46:47]
	s_waitcnt vmcnt(8)
	s_waitcnt lgkmcnt(0)
	s_barrier
; #define PG8_STAGE(bufoff, gbase, voff) do { _Pragma("unroll") for (int _i = 0; _i < 2; ++_i) \
;         __builtin_amdgcn_global_load_lds((const unsigned*)((const char*)(gbase) + (voff)[_i]), (LAS unsigned*)(lds + (bufoff) + ldsw + _i * 8192), 16, 0, 0); } while (0)
; #define PG8_LDA(dst, b, h) do { _Pragma("unroll") for (int m = 0; m < 4; ++m) _Pragma("unroll") for (int k = 0; k < 2; ++k) dst[m][k] = *(const LAS bf16x8*)(lds + PG8_SA(b, h) + aoff + m * 2048 + k * 1024); } while (0)
; #define PG8_LDB(dst, b, h) do { _Pragma("unroll") for (int n = 0; n < 2; ++n) _Pragma("unroll") for (int k = 0; k < 2; ++k) dst[n][k] = *(const LAS bf16x8*)(lds + PG8_SB(b, h) + boff + n * 2048 + k * 1024); } while (0)
; #define PG8_MMA(ai, bj, At, Bt) do { __builtin_amdgcn_s_setprio(1); _Pragma("unroll") for (int m = 0; m < 4; ++m) _Pragma("unroll") for (int n = 0; n < 2; ++n) _Pragma("unroll") for (int k = 0; k < 2; ++k) \
;         acc[ai][bj][m][n] = __builtin_amdgcn_mfma_f32_16x16x32_bf16(Bt[n][k], At[m][k], acc[ai][bj][m][n], 0, 0, 0); __builtin_amdgcn_s_setprio(0); } while (0)
; #define PG8_WAIT_V(n) asm volatile("s_waitcnt vmcnt(" #n ")" ::: "memory")
; #define PG8_WAIT_L(n) asm volatile("s_waitcnt lgkmcnt(" #n ")" ::: "memory")
; #define PG8_BAR __builtin_amdgcn_s_barrier()
; #define PG8_SCHED __builtin_amdgcn_sched_barrier(0)
; template <class Epi, bool ALIGN_EPI, bool SPLITA>
; __device__ __forceinline__ void gemm_phase(LAS unsigned char* lds, const Gemm g, const StaticOrder& S, const Epi& E) {
;     ...
;             PG8_WAIT_V(8); PG8_WAIT_L(0); PG8_BAR; PG8_MMA(0, 0, At, B0); PG8_MMA(0, 1, At, B1); PG8_BAR; PG8_SCHED;
;             PG8_LDA(At, 0, 1); PG8_STAGE(PG8_SB(0, 0), b2, voffB); PG8_STAGE(PG8_SB(0, 1), b2 + hstepB, voffB); PG8_STAGE(PG8_SA(0, 0), a2, vo2);
;             PG8_WAIT_V(8); PG8_WAIT_L(0); PG8_BAR; PG8_MMA(1, 0, At, B0); PG8_MMA(1, 1, At, B1); PG8_BAR; PG8_SCHED;
;             PG8_LDB(B0, 1, 0); PG8_LDB(B1, 1, 1); PG8_SCHED; PG8_LDA(At, 1, 0); PG8_STAGE(PG8_SA(0, 1), a2h, vo2);
;             PG8_WAIT_V(8); PG8_WAIT_L(0); PG8_BAR; PG8_MMA(0, 0, At, B0); PG8_MMA(0, 1, At, B1); PG8_BAR; PG8_SCHED;
	s_setprio 1
	s_waitcnt lgkmcnt(0)
	v_mfma_f32_16x16x32_bf16 v[54:57], v[146:149], v[188:191], 0
	v_mfma_f32_16x16x32_bf16 v[50:53], v[164:167], v[188:191], 0
	v_mfma_f32_16x16x32_bf16 v[22:25], v[146:149], v[196:199], 0
	v_mfma_f32_16x16x32_bf16 v[18:21], v[164:167], v[196:199], 0
	v_mfma_f32_16x16x32_bf16 v[14:17], v[146:149], v[204:207], 0
	v_mfma_f32_16x16x32_bf16 v[10:13], v[164:167], v[204:207], 0
	v_mfma_f32_16x16x32_bf16 v[6:9], v[146:149], v[212:215], 0
	v_mfma_f32_16x16x32_bf16 v[2:5], v[164:167], v[212:215], 0
	v_mfma_f32_16x16x32_bf16 v[54:57], v[156:159], v[192:195], v[54:57]
	v_mfma_f32_16x16x32_bf16 v[50:53], v[168:171], v[192:195], v[50:53]
	v_mfma_f32_16x16x32_bf16 v[22:25], v[156:159], v[200:203], v[22:25]
	v_mfma_f32_16x16x32_bf16 v[18:21], v[168:171], v[200:203], v[18:21]
	v_mfma_f32_16x16x32_bf16 v[14:17], v[156:159], v[208:211], v[14:17]
	v_mfma_f32_16x16x32_bf16 v[10:13], v[168:171], v[208:211], v[10:13]
	v_mfma_f32_16x16x32_bf16 v[6:9], v[156:159], v[216:219], v[6:9]
	v_mfma_f32_16x16x32_bf16 v[2:5], v[168:171], v[216:219], v[2:5]
	s_setprio 0
	s_setprio 1
	v_mfma_f32_16x16x32_bf16 v[38:41], v[172:175], v[188:191], 0
	v_mfma_f32_16x16x32_bf16 v[34:37], v[180:183], v[188:191], 0
	v_mfma_f32_16x16x32_bf16 v[58:61], v[172:175], v[196:199], 0
	v_mfma_f32_16x16x32_bf16 v[62:65], v[180:183], v[196:199], 0
	v_mfma_f32_16x16x32_bf16 v[42:45], v[172:175], v[204:207], 0
	v_mfma_f32_16x16x32_bf16 v[46:49], v[180:183], v[204:207], 0
	v_mfma_f32_16x16x32_bf16 v[26:29], v[172:175], v[212:215], 0
	v_mfma_f32_16x16x32_bf16 v[30:33], v[180:183], v[212:215], 0
	v_mfma_f32_16x16x32_bf16 v[38:41], v[176:179], v[192:195], v[38:41]
	v_mfma_f32_16x16x32_bf16 v[34:37], v[184:187], v[192:195], v[34:37]
	v_mfma_f32_16x16x32_bf16 v[58:61], v[176:179], v[200:203], v[58:61]
	v_mfma_f32_16x16x32_bf16 v[62:65], v[184:187], v[200:203], v[62:65]
	v_mfma_f32_16x16x32_bf16 v[42:45], v[176:179], v[208:211], v[42:45]
	v_mfma_f32_16x16x32_bf16 v[46:49], v[184:187], v[208:211], v[46:49]
	v_mfma_f32_16x16x32_bf16 v[26:29], v[176:179], v[216:219], v[26:29]
	v_mfma_f32_16x16x32_bf16 v[30:33], v[184:187], v[216:219], v[30:33]
	s_setprio 0
	s_barrier
	s_add_i32 s89, 0, 0x18000
	v_add_u32_e32 v155, s89, v150
	s_add_i32 s92, 0, 0x1c000
	ds_read_b128 v[146:149], v155
	ds_read_b128 v[156:159], v155 offset:1024
	ds_read_b128 v[164:167], v155 offset:2048
	ds_read_b128 v[168:171], v155 offset:3072
	v_add_u32_e32 v155, s92, v150
	ds_read_b128 v[172:175], v155
	ds_read_b128 v[176:179], v155 offset:1024
	ds_read_b128 v[180:183], v155 offset:2048
	ds_read_b128 v[184:187], v155 offset:3072
	s_add_u32 s46, s46, 0x40000
	s_addc_u32 s47, s47, 0
	s_mov_b32 m0, s61
	ds_read_b128 v[188:191], v154 offset:32768
	ds_read_b128 v[192:195], v154 offset:33792
	ds_read_b128 v[196:199], v154 offset:34816
	ds_read_b128 v[200:203], v154 offset:35840
	ds_read_b128 v[204:207], v154 offset:36864
	ds_read_b128 v[208:211], v154 offset:37888
	ds_read_b128 v[212:215], v154 offset:38912
	ds_read_b128 v[216:219], v154 offset:39936
	global_load_lds_dwordx4 v136, s[46:47]
	s_mov_b32 m0, s64
	s_nop 0
	global_load_lds_dwordx4 v132, s[46:47]
	s_waitcnt vmcnt(8)
	s_waitcnt lgkmcnt(0)
	s_barrier
	s_setprio 1
	s_waitcnt lgkmcnt(0)
	v_mfma_f32_16x16x32_bf16 v[126:129], v[146:149], v[188:191], v[126:129]
	v_mfma_f32_16x16x32_bf16 v[122:125], v[164:167], v[188:191], v[122:125]
	v_mfma_f32_16x16x32_bf16 v[110:113], v[146:149], v[196:199], v[110:113]
	v_mfma_f32_16x16x32_bf16 v[106:109], v[164:167], v[196:199], v[106:109]
	v_mfma_f32_16x16x32_bf16 v[94:97], v[146:149], v[204:207], v[94:97]
	v_mfma_f32_16x16x32_bf16 v[90:93], v[164:167], v[204:207], v[90:93]
	v_mfma_f32_16x16x32_bf16 v[78:81], v[146:149], v[212:215], v[78:81]
	v_mfma_f32_16x16x32_bf16 v[74:77], v[164:167], v[212:215], v[74:77]
	v_mfma_f32_16x16x32_bf16 v[126:129], v[156:159], v[192:195], v[126:129]
	v_mfma_f32_16x16x32_bf16 v[122:125], v[168:171], v[192:195], v[122:125]
	v_mfma_f32_16x16x32_bf16 v[110:113], v[156:159], v[200:203], v[110:113]
	v_mfma_f32_16x16x32_bf16 v[106:109], v[168:171], v[200:203], v[106:109]
	v_mfma_f32_16x16x32_bf16 v[94:97], v[156:159], v[208:211], v[94:97]
	v_mfma_f32_16x16x32_bf16 v[90:93], v[168:171], v[208:211], v[90:93]
	v_mfma_f32_16x16x32_bf16 v[78:81], v[156:159], v[216:219], v[78:81]
	v_mfma_f32_16x16x32_bf16 v[74:77], v[168:171], v[216:219], v[74:77]
	s_setprio 0
	s_setprio 1
	v_mfma_f32_16x16x32_bf16 v[118:121], v[172:175], v[188:191], v[118:121]
	v_mfma_f32_16x16x32_bf16 v[114:117], v[180:183], v[188:191], v[114:117]
	v_mfma_f32_16x16x32_bf16 v[102:105], v[172:175], v[196:199], v[102:105]
	v_mfma_f32_16x16x32_bf16 v[98:101], v[180:183], v[196:199], v[98:101]
	v_mfma_f32_16x16x32_bf16 v[86:89], v[172:175], v[204:207], v[86:89]
	v_mfma_f32_16x16x32_bf16 v[82:85], v[180:183], v[204:207], v[82:85]
	v_mfma_f32_16x16x32_bf16 v[70:73], v[172:175], v[212:215], v[70:73]
	v_mfma_f32_16x16x32_bf16 v[66:69], v[180:183], v[212:215], v[66:69]
	v_mfma_f32_16x16x32_bf16 v[118:121], v[176:179], v[192:195], v[118:121]
	v_mfma_f32_16x16x32_bf16 v[114:117], v[184:187], v[192:195], v[114:117]
	v_mfma_f32_16x16x32_bf16 v[102:105], v[176:179], v[200:203], v[102:105]
	v_mfma_f32_16x16x32_bf16 v[98:101], v[184:187], v[200:203], v[98:101]
	v_mfma_f32_16x16x32_bf16 v[86:89], v[176:179], v[208:211], v[86:89]
	v_mfma_f32_16x16x32_bf16 v[82:85], v[184:187], v[208:211], v[82:85]
	v_mfma_f32_16x16x32_bf16 v[70:73], v[176:179], v[216:219], v[70:73]
	v_mfma_f32_16x16x32_bf16 v[66:69], v[184:187], v[216:219], v[66:69]
	s_setprio 0
	s_barrier
; #define PG8_STAGE(bufoff, gbase, voff) do { _Pragma("unroll") for (int _i = 0; _i < 2; ++_i) \
;         __builtin_amdgcn_global_load_lds((const unsigned*)((const char*)(gbase) + (voff)[_i]), (LAS unsigned*)(lds + (bufoff) + ldsw + _i * 8192), 16, 0, 0); } while (0)
; #define PG8_LDA(dst, b, h) do { _Pragma("unroll") for (int m = 0; m < 4; ++m) _Pragma("unroll") for (int k = 0; k < 2; ++k) dst[m][k] = *(const LAS bf16x8*)(lds + PG8_SA(b, h) + aoff + m * 2048 + k * 1024); } while (0)
; #define PG8_MMA(ai, bj, At, Bt) do { __builtin_amdgcn_s_setprio(1); _Pragma("unroll") for (int m = 0; m < 4; ++m) _Pragma("unroll") for (int n = 0; n < 2; ++n) _Pragma("unroll") for (int k = 0; k < 2; ++k) \
;         acc[ai][bj][m][n] = __builtin_amdgcn_mfma_f32_16x16x32_bf16(Bt[n][k], At[m][k], acc[ai][bj][m][n], 0, 0, 0); __builtin_amdgcn_s_setprio(0); } while (0)
; #define PG8_WAIT_V(n) asm volatile("s_waitcnt vmcnt(" #n ")" ::: "memory")
; #define PG8_WAIT_L(n) asm volatile("s_waitcnt lgkmcnt(" #n ")" ::: "memory")
; #define PG8_BAR __builtin_amdgcn_s_barrier()
; #define PG8_SCHED __builtin_amdgcn_sched_barrier(0)
; template <class Epi, bool ALIGN_EPI, bool SPLITA>
; __device__ __forceinline__ void gemm_phase(LAS unsigned char* lds, const Gemm g, const StaticOrder& S, const Epi& E) {
;     ...
;             PG8_LDA(At, 1, 1); PG8_STAGE(PG8_SB(1, 0), b3, voffB); PG8_STAGE(PG8_SB(1, 1), b3 + hstepB, voffB); PG8_STAGE(PG8_SA(1, 0), a3, vo2);
;             PG8_WAIT_V(8); PG8_WAIT_L(0); PG8_BAR; PG8_MMA(1, 0, At, B0); PG8_MMA(1, 1, At, B1); PG8_BAR; PG8_SCHED;
	s_add_i32 s46, s89, s33
	s_mov_b32 m0, s46
	ds_read_b128 v[188:191], v154 offset:49152
	ds_read_b128 v[192:195], v154 offset:50176
	ds_read_b128 v[196:199], v154 offset:51200
	ds_read_b128 v[200:203], v154 offset:52224
	ds_read_b128 v[204:207], v154 offset:53248
	ds_read_b128 v[208:211], v154 offset:54272
	ds_read_b128 v[212:215], v154 offset:55296
	ds_read_b128 v[216:219], v154 offset:56320
	global_load_lds_dwordx4 v134, s[98:99]
	s_add_i32 m0, s46, 0x2000
	s_add_u32 s44, s44, 0x200080
	s_addc_u32 s45, s45, 0
	s_add_i32 s46, s92, s33
	global_load_lds_dwordx4 v130, s[98:99]
	s_mov_b32 m0, s46
	s_nop 0
	global_load_lds_dwordx4 v134, s[44:45]
	s_add_i32 m0, s46, 0x2000
	s_nop 0
	global_load_lds_dwordx4 v130, s[44:45]
	s_mov_b32 m0, s72
	s_nop 0
	global_load_lds_dwordx4 v136, s[100:101]
	s_mov_b32 m0, s73
	s_nop 0
	global_load_lds_dwordx4 v132, s[100:101]
	s_waitcnt vmcnt(8)
	s_waitcnt lgkmcnt(0)
	s_barrier
	s_setprio 1
	s_waitcnt lgkmcnt(0)
	v_mfma_f32_16x16x32_bf16 v[54:57], v[146:149], v[188:191], v[54:57]
	v_mfma_f32_16x16x32_bf16 v[50:53], v[164:167], v[188:191], v[50:53]
	v_mfma_f32_16x16x32_bf16 v[22:25], v[146:149], v[196:199], v[22:25]
	v_mfma_f32_16x16x32_bf16 v[18:21], v[164:167], v[196:199], v[18:21]
	v_mfma_f32_16x16x32_bf16 v[14:17], v[146:149], v[204:207], v[14:17]
	v_mfma_f32_16x16x32_bf16 v[10:13], v[164:167], v[204:207], v[10:13]
	v_mfma_f32_16x16x32_bf16 v[6:9], v[146:149], v[212:215], v[6:9]
	v_mfma_f32_16x16x32_bf16 v[2:5], v[164:167], v[212:215], v[2:5]
	v_mfma_f32_16x16x32_bf16 v[54:57], v[156:159], v[192:195], v[54:57]
	v_mfma_f32_16x16x32_bf16 v[50:53], v[168:171], v[192:195], v[50:53]
	v_mfma_f32_16x16x32_bf16 v[22:25], v[156:159], v[200:203], v[22:25]
	v_mfma_f32_16x16x32_bf16 v[18:21], v[168:171], v[200:203], v[18:21]
	v_mfma_f32_16x16x32_bf16 v[14:17], v[156:159], v[208:211], v[14:17]
	v_mfma_f32_16x16x32_bf16 v[10:13], v[168:171], v[208:211], v[10:13]
	v_mfma_f32_16x16x32_bf16 v[6:9], v[156:159], v[216:219], v[6:9]
	v_mfma_f32_16x16x32_bf16 v[2:5], v[168:171], v[216:219], v[2:5]
	s_setprio 0
	s_setprio 1
	v_mfma_f32_16x16x32_bf16 v[38:41], v[172:175], v[188:191], v[38:41]
	v_mfma_f32_16x16x32_bf16 v[34:37], v[180:183], v[188:191], v[34:37]
	v_mfma_f32_16x16x32_bf16 v[58:61], v[172:175], v[196:199], v[58:61]
	v_mfma_f32_16x16x32_bf16 v[62:65], v[180:183], v[196:199], v[62:65]
	v_mfma_f32_16x16x32_bf16 v[42:45], v[172:175], v[204:207], v[42:45]
	v_mfma_f32_16x16x32_bf16 v[46:49], v[180:183], v[204:207], v[46:49]
	v_mfma_f32_16x16x32_bf16 v[26:29], v[172:175], v[212:215], v[26:29]
	v_mfma_f32_16x16x32_bf16 v[30:33], v[180:183], v[212:215], v[30:33]
	v_mfma_f32_16x16x32_bf16 v[38:41], v[176:179], v[192:195], v[38:41]
	v_mfma_f32_16x16x32_bf16 v[34:37], v[184:187], v[192:195], v[34:37]
	v_mfma_f32_16x16x32_bf16 v[58:61], v[176:179], v[200:203], v[58:61]
	v_mfma_f32_16x16x32_bf16 v[62:65], v[184:187], v[200:203], v[62:65]
	v_mfma_f32_16x16x32_bf16 v[42:45], v[176:179], v[208:211], v[42:45]
	v_mfma_f32_16x16x32_bf16 v[46:49], v[184:187], v[208:211], v[46:49]
	v_mfma_f32_16x16x32_bf16 v[26:29], v[176:179], v[216:219], v[26:29]
	v_mfma_f32_16x16x32_bf16 v[30:33], v[184:187], v[216:219], v[30:33]
	s_setprio 0
	s_barrier
	s_add_i32 s91, s91, 2
	s_add_u32 s0, s0, 0x100
	s_addc_u32 s1, s1, 0
	s_add_u32 s29, s29, 0x100
	s_addc_u32 s90, s90, 0

; template <class Epi, bool ALIGN_EPI, bool SPLITA>
; __device__ __forceinline__ void gemm_phase(LAS unsigned char* lds, const Gemm g, const StaticOrder& S, const Epi& E) {
;     ...
;         const bool has_next = S.next(ui + 1, nxt);
;         const char* nA = has_next ? baseA1(nxt) : cA;
;         const char* nB = has_next ? baseB(nxt) : cB;
;         const bool mirN = has_next ? mirrored(nxt) : mirC;
;         for (int t = 0; t < nt; t += 2) {
;             const bool last = (t == nt - 2);
;             if constexpr (Epi::MIDK) { if (t == g.ksplit) E.mid(acc, cur, wr, wc, fr, fq); }
;             const char *a1, *a2;
;             if constexpr (SPLITA) {
;                 a1 = (t + 1 < g.ksplit) ? cA + (size_t)(t + 1) * kstep : cA2 + (size_t)(t + 1 - g.ksplit) * 2048;
;                 a2 = last ? nA : ((t + 2 < g.ksplit) ? cA + (size_t)(t + 2) * kstep : cA2 + (size_t)(t + 2 - g.ksplit) * 2048);
;             } else { a1 = cA + kofs(t + 1); a2 = last ? nA : cA + kofs(t + 2); }
;             const char* b2 = last ? nB : cB + (size_t)(t + 2) * kstepB;
;             const bool s2a = SPLITA && (t + 1 >= g.ksplit), s2b = SPLITA && !last && (t + 2 >= g.ksplit);
;             const char* a3 = a2 + ((Epi::KSUB || s2b) ? (size_t)2048 : kstep); const char* b3 = b2 + kstepB;
;             const bool m1 = SPLITA && mirC && (t + 1 < g.ksplit), m2 = SPLITA && (last ? mirN : (mirC && (t + 2 < g.ksplit)));
;             const unsigned vo1[2] = {s2a ? voffA2[0] : m1 ? voffAm[0] : voffA[0], s2a ? voffA2[1] : m1 ? voffAm[1] : voffA[1]}, vo2[2] = {s2b ? voffA2[0] : m2 ? voffAm[0] : voffA[0], s2b ? voffA2[1] : m2 ? voffAm[1] : voffA[1]};
;             const char* a1h = m1 ? a1 - hstepA : a1 + hstepA; const char* a2h = m2 ? a2 - hstepA : a2 + hstepA;
;             PG8_LDB(B0, 0, 0); PG8_LDB(B1, 0, 1); PG8_SCHED; PG8_LDA(At, 0, 0); PG8_STAGE(PG8_SA(1, 1), a1h, vo1);
;             PG8_WAIT_V(8); PG8_WAIT_L(0); PG8_BAR; PG8_MMA(0, 0, At, B0); PG8_MMA(0, 1, At, B1); PG8_BAR; PG8_SCHED;
;             PG8_LDA(At, 0, 1); PG8_STAGE(PG8_SB(0, 0), b2, voffB); PG8_STAGE(PG8_SB(0, 1), b2 + hstepB, voffB); PG8_STAGE(PG8_SA(0, 0), a2, vo2);
;             PG8_WAIT_V(8); PG8_WAIT_L(0); PG8_BAR; PG8_MMA(1, 0, At, B0); PG8_MMA(1, 1, At, B1); PG8_BAR; PG8_SCHED;
;             PG8_LDB(B0, 1, 0); PG8_LDB(B1, 1, 1); PG8_SCHED; PG8_LDA(At, 1, 0); PG8_STAGE(PG8_SA(0, 1), a2h, vo2);
.LBB0_414:
	s_add_u32 s48, s48, 0x40080
	s_addc_u32 s49, s49, 0
	s_add_u32 s5, s50, 0x100
	s_addc_u32 s11, s51, 0
	s_mov_b32 s31, -2
	ds_read_b128 v[146:149], v156
	ds_read_b128 v[150:153], v156 offset:1024
	ds_read_b128 v[160:163], v156 offset:2048
	ds_read_b128 v[164:167], v156 offset:3072
	ds_read_b128 v[168:171], v157
	ds_read_b128 v[172:175], v157 offset:1024
	ds_read_b128 v[176:179], v157 offset:2048
	ds_read_b128 v[180:183], v157 offset:3072
	s_add_u32 s12, s48, 0xfffc0080
	s_addc_u32 s13, s49, -1
	s_cmp_eq_u32 s31, 12
	s_cselect_b32 s53, s1, s13
	s_cselect_b32 s52, s0, s12
	s_cselect_b32 s51, s47, s11
	s_cselect_b32 s50, s46, s5
	s_add_i32 m0, s54, 0xc000
	ds_read_b128 v[184:187], v158
	ds_read_b128 v[188:191], v158 offset:1024
	ds_read_b128 v[192:195], v158 offset:2048
	ds_read_b128 v[196:199], v158 offset:3072
	ds_read_b128 v[200:203], v158 offset:4096
	ds_read_b128 v[204:207], v158 offset:5120
	ds_read_b128 v[208:211], v158 offset:6144
	ds_read_b128 v[212:215], v158 offset:7168
	global_load_lds_dwordx4 v138, s[48:49]
	s_add_i32 m0, s54, 0xe000
	s_nop 0
	global_load_lds_dwordx4 v140, s[48:49]
	s_waitcnt vmcnt(8)
	s_waitcnt lgkmcnt(0)
	s_barrier
	s_setprio 1
	s_waitcnt lgkmcnt(0)
	v_mfma_f32_16x16x32_bf16 v[126:129], v[146:149], v[184:187], 0
	v_mfma_f32_16x16x32_bf16 v[122:125], v[160:163], v[184:187], 0
	v_mfma_f32_16x16x32_bf16 v[110:113], v[146:149], v[192:195], 0
	v_mfma_f32_16x16x32_bf16 v[106:109], v[160:163], v[192:195], 0
	v_mfma_f32_16x16x32_bf16 v[94:97], v[146:149], v[200:203], 0
	v_mfma_f32_16x16x32_bf16 v[90:93], v[160:163], v[200:203], 0
	v_mfma_f32_16x16x32_bf16 v[78:81], v[146:149], v[208:211], 0
	v_mfma_f32_16x16x32_bf16 v[74:77], v[160:163], v[208:211], 0
	v_mfma_f32_16x16x32_bf16 v[126:129], v[150:153], v[188:191], v[126:129]
	v_mfma_f32_16x16x32_bf16 v[122:125], v[164:167], v[188:191], v[122:125]
	v_mfma_f32_16x16x32_bf16 v[110:113], v[150:153], v[196:199], v[110:113]
	v_mfma_f32_16x16x32_bf16 v[106:109], v[164:167], v[196:199], v[106:109]
	v_mfma_f32_16x16x32_bf16 v[94:97], v[150:153], v[204:207], v[94:97]
	v_mfma_f32_16x16x32_bf16 v[90:93], v[164:167], v[204:207], v[90:93]
	v_mfma_f32_16x16x32_bf16 v[78:81], v[150:153], v[212:215], v[78:81]
	v_mfma_f32_16x16x32_bf16 v[74:77], v[164:167], v[212:215], v[74:77]
	s_setprio 0
	s_setprio 1
	v_mfma_f32_16x16x32_bf16 v[118:121], v[168:171], v[184:187], 0
	v_mfma_f32_16x16x32_bf16 v[114:117], v[176:179], v[184:187], 0
	v_mfma_f32_16x16x32_bf16 v[102:105], v[168:171], v[192:195], 0
	v_mfma_f32_16x16x32_bf16 v[98:101], v[176:179], v[192:195], 0
	v_mfma_f32_16x16x32_bf16 v[86:89], v[168:171], v[200:203], 0
	v_mfma_f32_16x16x32_bf16 v[82:85], v[176:179], v[200:203], 0
	v_mfma_f32_16x16x32_bf16 v[70:73], v[168:171], v[208:211], 0
	v_mfma_f32_16x16x32_bf16 v[66:69], v[176:179], v[208:211], 0
	v_mfma_f32_16x16x32_bf16 v[118:121], v[172:175], v[188:191], v[118:121]
	v_mfma_f32_16x16x32_bf16 v[114:117], v[180:183], v[188:191], v[114:117]
	v_mfma_f32_16x16x32_bf16 v[102:105], v[172:175], v[196:199], v[102:105]
	v_mfma_f32_16x16x32_bf16 v[98:101], v[180:183], v[196:199], v[98:101]
	v_mfma_f32_16x16x32_bf16 v[86:89], v[172:175], v[204:207], v[86:89]
	v_mfma_f32_16x16x32_bf16 v[82:85], v[180:183], v[204:207], v[82:85]
	v_mfma_f32_16x16x32_bf16 v[70:73], v[172:175], v[212:215], v[70:73]
	v_mfma_f32_16x16x32_bf16 v[66:69], v[180:183], v[212:215], v[66:69]
	s_setprio 0
	s_barrier
	s_add_u32 s98, s50, s18
	s_addc_u32 s99, s51, s19
	s_add_u32 s100, s52, s18
	s_addc_u32 s101, s53, s19
	s_add_i32 s12, s65, s33
	s_mov_b32 m0, s12
	ds_read_b128 v[184:187], v158 offset:16384
	ds_read_b128 v[188:191], v158 offset:17408
	ds_read_b128 v[192:195], v158 offset:18432
	ds_read_b128 v[196:199], v158 offset:19456
	ds_read_b128 v[200:203], v158 offset:20480
	ds_read_b128 v[204:207], v158 offset:21504
	ds_read_b128 v[208:211], v158 offset:22528
	ds_read_b128 v[212:215], v158 offset:23552
	global_load_lds_dwordx4 v132, s[50:51]
	s_add_i32 m0, s12, 0x2000
	s_add_u32 s76, s50, 0xc00000
	s_addc_u32 s77, s51, 0
	s_add_i32 s12, s72, s33
	global_load_lds_dwordx4 v136, s[50:51]
	s_mov_b32 m0, s12
	s_nop 0
	global_load_lds_dwordx4 v132, s[76:77]
	s_add_i32 m0, s12, 0x2000
	s_nop 0
	global_load_lds_dwordx4 v136, s[76:77]
	s_mov_b32 m0, s54
	s_nop 0
	global_load_lds_dwordx4 v130, s[52:53]
	s_mov_b32 m0, s55
	s_nop 0
	global_load_lds_dwordx4 v134, s[52:53]
	s_waitcnt vmcnt(8)
	s_waitcnt lgkmcnt(0)
	s_barrier
	s_setprio 1
	s_waitcnt lgkmcnt(0)
	v_mfma_f32_16x16x32_bf16 v[62:65], v[146:149], v[184:187], 0
	v_mfma_f32_16x16x32_bf16 v[58:61], v[160:163], v[184:187], 0
	v_mfma_f32_16x16x32_bf16 v[38:41], v[146:149], v[192:195], 0
	v_mfma_f32_16x16x32_bf16 v[34:37], v[160:163], v[192:195], 0
	v_mfma_f32_16x16x32_bf16 v[22:25], v[146:149], v[200:203], 0
	v_mfma_f32_16x16x32_bf16 v[18:21], v[160:163], v[200:203], 0
	v_mfma_f32_16x16x32_bf16 v[6:9], v[146:149], v[208:211], 0
	v_mfma_f32_16x16x32_bf16 v[2:5], v[160:163], v[208:211], 0
	v_mfma_f32_16x16x32_bf16 v[62:65], v[150:153], v[188:191], v[62:65]
	v_mfma_f32_16x16x32_bf16 v[58:61], v[164:167], v[188:191], v[58:61]
	v_mfma_f32_16x16x32_bf16 v[38:41], v[150:153], v[196:199], v[38:41]
	v_mfma_f32_16x16x32_bf16 v[34:37], v[164:167], v[196:199], v[34:37]
	v_mfma_f32_16x16x32_bf16 v[22:25], v[150:153], v[204:207], v[22:25]
	v_mfma_f32_16x16x32_bf16 v[18:21], v[164:167], v[204:207], v[18:21]
	v_mfma_f32_16x16x32_bf16 v[6:9], v[150:153], v[212:215], v[6:9]
	v_mfma_f32_16x16x32_bf16 v[2:5], v[164:167], v[212:215], v[2:5]
	s_setprio 0
	s_setprio 1
	v_mfma_f32_16x16x32_bf16 v[54:57], v[168:171], v[184:187], 0
	v_mfma_f32_16x16x32_bf16 v[50:53], v[176:179], v[184:187], 0
	v_mfma_f32_16x16x32_bf16 v[42:45], v[168:171], v[192:195], 0
	v_mfma_f32_16x16x32_bf16 v[46:49], v[176:179], v[192:195], 0
	v_mfma_f32_16x16x32_bf16 v[26:29], v[168:171], v[200:203], 0
	v_mfma_f32_16x16x32_bf16 v[30:33], v[176:179], v[200:203], 0
	v_mfma_f32_16x16x32_bf16 v[10:13], v[168:171], v[208:211], 0
	v_mfma_f32_16x16x32_bf16 v[14:17], v[176:179], v[208:211], 0
	v_mfma_f32_16x16x32_bf16 v[54:57], v[172:175], v[188:191], v[54:57]
	v_mfma_f32_16x16x32_bf16 v[50:53], v[180:183], v[188:191], v[50:53]
	v_mfma_f32_16x16x32_bf16 v[42:45], v[172:175], v[196:199], v[42:45]
	v_mfma_f32_16x16x32_bf16 v[46:49], v[180:183], v[196:199], v[46:49]
	v_mfma_f32_16x16x32_bf16 v[26:29], v[172:175], v[204:207], v[26:29]
	v_mfma_f32_16x16x32_bf16 v[30:33], v[180:183], v[204:207], v[30:33]
	v_mfma_f32_16x16x32_bf16 v[10:13], v[172:175], v[212:215], v[10:13]
	v_mfma_f32_16x16x32_bf16 v[14:17], v[180:183], v[212:215], v[14:17]
	s_setprio 0
	s_barrier
; #define PG8_STAGE(bufoff, gbase, voff) do { _Pragma("unroll") for (int _i = 0; _i < 2; ++_i) \
;         __builtin_amdgcn_global_load_lds((const unsigned*)((const char*)(gbase) + (voff)[_i]), (LAS unsigned*)(lds + (bufoff) + ldsw + _i * 8192), 16, 0, 0); } while (0)
; #define PG8_LDA(dst, b, h) do { _Pragma("unroll") for (int m = 0; m < 4; ++m) _Pragma("unroll") for (int k = 0; k < 2; ++k) dst[m][k] = *(const LAS bf16x8*)(lds + PG8_SA(b, h) + aoff + m * 2048 + k * 1024); } while (0)
; #define PG8_LDB(dst, b, h) do { _Pragma("unroll") for (int n = 0; n < 2; ++n) _Pragma("unroll") for (int k = 0; k < 2; ++k) dst[n][k] = *(const LAS bf16x8*)(lds + PG8_SB(b, h) + boff + n * 2048 + k * 1024); } while (0)
; #define PG8_MMA(ai, bj, At, Bt) do { __builtin_amdgcn_s_setprio(1); _Pragma("unroll") for (int m = 0; m < 4; ++m) _Pragma("unroll") for (int n = 0; n < 2; ++n) _Pragma("unroll") for (int k = 0; k < 2; ++k) \
;         acc[ai][bj][m][n] = __builtin_amdgcn_mfma_f32_16x16x32_bf16(Bt[n][k], At[m][k], acc[ai][bj][m][n], 0, 0, 0); __builtin_amdgcn_s_setprio(0); } while (0)
; #define PG8_WAIT_V(n) asm volatile("s_waitcnt vmcnt(" #n ")" ::: "memory")
; #define PG8_WAIT_L(n) asm volatile("s_waitcnt lgkmcnt(" #n ")" ::: "memory")
; #define PG8_BAR __builtin_amdgcn_s_barrier()
; #define PG8_SCHED __builtin_amdgcn_sched_barrier(0)
; template <class Epi, bool ALIGN_EPI, bool SPLITA>
; __device__ __forceinline__ void gemm_phase(LAS unsigned char* lds, const Gemm g, const StaticOrder& S, const Epi& E) {
;     ...
;             PG8_LDB(B0, 1, 0); PG8_LDB(B1, 1, 1); PG8_SCHED; PG8_LDA(At, 1, 0); PG8_STAGE(PG8_SA(0, 1), a2h, vo2);
;             PG8_WAIT_V(8); PG8_WAIT_L(0); PG8_BAR; PG8_MMA(0, 0, At, B0); PG8_MMA(0, 1, At, B1); PG8_BAR; PG8_SCHED;
;             PG8_LDA(At, 1, 1); PG8_STAGE(PG8_SB(1, 0), b3, voffB); PG8_STAGE(PG8_SB(1, 1), b3 + hstepB, voffB); PG8_STAGE(PG8_SA(1, 0), a3, vo2);
;             PG8_WAIT_V(8); PG8_WAIT_L(0); PG8_BAR; PG8_MMA(1, 0, At, B0); PG8_MMA(1, 1, At, B1); PG8_BAR; PG8_SCHED;
	s_add_i32 s12, 0, 0x18000
	v_add_u32_e32 v159, s12, v154
	s_add_i32 s13, 0, 0x1c000
	ds_read_b128 v[146:149], v159
	ds_read_b128 v[150:153], v159 offset:1024
	ds_read_b128 v[160:163], v159 offset:2048
	ds_read_b128 v[164:167], v159 offset:3072
	v_add_u32_e32 v159, s13, v154
	ds_read_b128 v[168:171], v159
	ds_read_b128 v[172:175], v159 offset:1024
	ds_read_b128 v[176:179], v159 offset:2048
	ds_read_b128 v[180:183], v159 offset:3072
	s_add_u32 s52, s52, 0x40000
	s_addc_u32 s53, s53, 0
	s_mov_b32 m0, s56
	ds_read_b128 v[184:187], v158 offset:32768
	ds_read_b128 v[188:191], v158 offset:33792
	ds_read_b128 v[192:195], v158 offset:34816
	ds_read_b128 v[196:199], v158 offset:35840
	ds_read_b128 v[200:203], v158 offset:36864
	ds_read_b128 v[204:207], v158 offset:37888
	ds_read_b128 v[208:211], v158 offset:38912
	ds_read_b128 v[212:215], v158 offset:39936
	global_load_lds_dwordx4 v130, s[52:53]
	s_mov_b32 m0, s57
	s_nop 0
	global_load_lds_dwordx4 v134, s[52:53]
	s_waitcnt vmcnt(8)
	s_waitcnt lgkmcnt(0)
	s_barrier
	s_setprio 1
	s_waitcnt lgkmcnt(0)
	v_mfma_f32_16x16x32_bf16 v[126:129], v[146:149], v[184:187], v[126:129]
	v_mfma_f32_16x16x32_bf16 v[122:125], v[160:163], v[184:187], v[122:125]
	v_mfma_f32_16x16x32_bf16 v[110:113], v[146:149], v[192:195], v[110:113]
	v_mfma_f32_16x16x32_bf16 v[106:109], v[160:163], v[192:195], v[106:109]
	v_mfma_f32_16x16x32_bf16 v[94:97], v[146:149], v[200:203], v[94:97]
	v_mfma_f32_16x16x32_bf16 v[90:93], v[160:163], v[200:203], v[90:93]
	v_mfma_f32_16x16x32_bf16 v[78:81], v[146:149], v[208:211], v[78:81]
	v_mfma_f32_16x16x32_bf16 v[74:77], v[160:163], v[208:211], v[74:77]
	v_mfma_f32_16x16x32_bf16 v[126:129], v[150:153], v[188:191], v[126:129]
	v_mfma_f32_16x16x32_bf16 v[122:125], v[164:167], v[188:191], v[122:125]
	v_mfma_f32_16x16x32_bf16 v[110:113], v[150:153], v[196:199], v[110:113]
	v_mfma_f32_16x16x32_bf16 v[106:109], v[164:167], v[196:199], v[106:109]
	v_mfma_f32_16x16x32_bf16 v[94:97], v[150:153], v[204:207], v[94:97]
	v_mfma_f32_16x16x32_bf16 v[90:93], v[164:167], v[204:207], v[90:93]
	v_mfma_f32_16x16x32_bf16 v[78:81], v[150:153], v[212:215], v[78:81]
	v_mfma_f32_16x16x32_bf16 v[74:77], v[164:167], v[212:215], v[74:77]
	s_setprio 0
	s_setprio 1
	v_mfma_f32_16x16x32_bf16 v[118:121], v[168:171], v[184:187], v[118:121]
	v_mfma_f32_16x16x32_bf16 v[114:117], v[176:179], v[184:187], v[114:117]
	v_mfma_f32_16x16x32_bf16 v[102:105], v[168:171], v[192:195], v[102:105]
	v_mfma_f32_16x16x32_bf16 v[98:101], v[176:179], v[192:195], v[98:101]
	v_mfma_f32_16x16x32_bf16 v[86:89], v[168:171], v[200:203], v[86:89]
	v_mfma_f32_16x16x32_bf16 v[82:85], v[176:179], v[200:203], v[82:85]
	v_mfma_f32_16x16x32_bf16 v[70:73], v[168:171], v[208:211], v[70:73]
	v_mfma_f32_16x16x32_bf16 v[66:69], v[176:179], v[208:211], v[66:69]
	v_mfma_f32_16x16x32_bf16 v[118:121], v[172:175], v[188:191], v[118:121]
	v_mfma_f32_16x16x32_bf16 v[114:117], v[180:183], v[188:191], v[114:117]
	v_mfma_f32_16x16x32_bf16 v[102:105], v[172:175], v[196:199], v[102:105]
	v_mfma_f32_16x16x32_bf16 v[98:101], v[180:183], v[196:199], v[98:101]
	v_mfma_f32_16x16x32_bf16 v[86:89], v[172:175], v[204:207], v[86:89]
	v_mfma_f32_16x16x32_bf16 v[82:85], v[180:183], v[204:207], v[82:85]
	v_mfma_f32_16x16x32_bf16 v[70:73], v[172:175], v[212:215], v[70:73]
	v_mfma_f32_16x16x32_bf16 v[66:69], v[180:183], v[212:215], v[66:69]
	s_setprio 0
	s_barrier
	s_add_i32 s12, s12, s33
	s_mov_b32 m0, s12
	ds_read_b128 v[184:187], v158 offset:49152
	ds_read_b128 v[188:191], v158 offset:50176
	ds_read_b128 v[192:195], v158 offset:51200
	ds_read_b128 v[196:199], v158 offset:52224
	ds_read_b128 v[200:203], v158 offset:53248
	ds_read_b128 v[204:207], v158 offset:54272
	ds_read_b128 v[208:211], v158 offset:55296
	ds_read_b128 v[212:215], v158 offset:56320
	global_load_lds_dwordx4 v132, s[98:99]
	s_add_i32 m0, s12, 0x2000
	s_add_u32 s50, s50, 0xc00080
	s_addc_u32 s51, s51, 0
	s_add_i32 s12, s13, s33
	global_load_lds_dwordx4 v136, s[98:99]
	s_mov_b32 m0, s12
	s_nop 0
	global_load_lds_dwordx4 v132, s[50:51]
	s_add_i32 m0, s12, 0x2000
	s_nop 0
	global_load_lds_dwordx4 v136, s[50:51]
	s_mov_b32 m0, s61
	s_nop 0
	global_load_lds_dwordx4 v130, s[100:101]
	s_mov_b32 m0, s64
	s_nop 0
	global_load_lds_dwordx4 v134, s[100:101]
	s_waitcnt vmcnt(8)
	s_waitcnt lgkmcnt(0)
	s_barrier
	s_setprio 1
	s_waitcnt lgkmcnt(0)
	v_mfma_f32_16x16x32_bf16 v[62:65], v[146:149], v[184:187], v[62:65]
	v_mfma_f32_16x16x32_bf16 v[58:61], v[160:163], v[184:187], v[58:61]
	v_mfma_f32_16x16x32_bf16 v[38:41], v[146:149], v[192:195], v[38:41]
	v_mfma_f32_16x16x32_bf16 v[34:37], v[160:163], v[192:195], v[34:37]
	v_mfma_f32_16x16x32_bf16 v[22:25], v[146:149], v[200:203], v[22:25]
	v_mfma_f32_16x16x32_bf16 v[18:21], v[160:163], v[200:203], v[18:21]
	v_mfma_f32_16x16x32_bf16 v[6:9], v[146:149], v[208:211], v[6:9]
	v_mfma_f32_16x16x32_bf16 v[2:5], v[160:163], v[208:211], v[2:5]
	v_mfma_f32_16x16x32_bf16 v[62:65], v[150:153], v[188:191], v[62:65]
	v_mfma_f32_16x16x32_bf16 v[58:61], v[164:167], v[188:191], v[58:61]
	v_mfma_f32_16x16x32_bf16 v[38:41], v[150:153], v[196:199], v[38:41]
	v_mfma_f32_16x16x32_bf16 v[34:37], v[164:167], v[196:199], v[34:37]
	v_mfma_f32_16x16x32_bf16 v[22:25], v[150:153], v[204:207], v[22:25]
	v_mfma_f32_16x16x32_bf16 v[18:21], v[164:167], v[204:207], v[18:21]
	v_mfma_f32_16x16x32_bf16 v[6:9], v[150:153], v[212:215], v[6:9]
	v_mfma_f32_16x16x32_bf16 v[2:5], v[164:167], v[212:215], v[2:5]
	s_setprio 0
	s_setprio 1
	v_mfma_f32_16x16x32_bf16 v[54:57], v[168:171], v[184:187], v[54:57]
	v_mfma_f32_16x16x32_bf16 v[50:53], v[176:179], v[184:187], v[50:53]
	v_mfma_f32_16x16x32_bf16 v[42:45], v[168:171], v[192:195], v[42:45]
	v_mfma_f32_16x16x32_bf16 v[46:49], v[176:179], v[192:195], v[46:49]
	v_mfma_f32_16x16x32_bf16 v[26:29], v[168:171], v[200:203], v[26:29]
	v_mfma_f32_16x16x32_bf16 v[30:33], v[176:179], v[200:203], v[30:33]
	v_mfma_f32_16x16x32_bf16 v[10:13], v[168:171], v[208:211], v[10:13]
	v_mfma_f32_16x16x32_bf16 v[14:17], v[176:179], v[208:211], v[14:17]
	v_mfma_f32_16x16x32_bf16 v[54:57], v[172:175], v[188:191], v[54:57]
	v_mfma_f32_16x16x32_bf16 v[50:53], v[180:183], v[188:191], v[50:53]
	v_mfma_f32_16x16x32_bf16 v[42:45], v[172:175], v[196:199], v[42:45]
	v_mfma_f32_16x16x32_bf16 v[46:49], v[180:183], v[196:199], v[46:49]
	v_mfma_f32_16x16x32_bf16 v[26:29], v[172:175], v[204:207], v[26:29]
	v_mfma_f32_16x16x32_bf16 v[30:33], v[180:183], v[204:207], v[30:33]
	v_mfma_f32_16x16x32_bf16 v[10:13], v[172:175], v[212:215], v[10:13]
	v_mfma_f32_16x16x32_bf16 v[14:17], v[180:183], v[212:215], v[14:17]
	s_setprio 0
	s_barrier
	s_add_i32 s31, s31, 2
	s_add_u32 s48, s48, 0x100
	s_addc_u32 s49, s49, 0
	s_add_u32 s5, s5, 0x100
	s_addc_u32 s11, s11, 0

; #define PG8_WAIT_V(n) asm volatile("s_waitcnt vmcnt(" #n ")" ::: "memory")
; #define PG8_BAR __builtin_amdgcn_s_barrier()
; template <class Epi, bool ALIGN_EPI, bool SPLITA>
; __device__ __forceinline__ void gemm_phase(LAS unsigned char* lds, const Gemm g, const StaticOrder& S, const Epi& E) {
;     ...
;         const bool has_next = S.next(ui + 1, nxt);
;         const char* nA = has_next ? baseA1(nxt) : cA;
;         const char* nB = has_next ? baseB(nxt) : cB;
;         const bool mirN = has_next ? mirrored(nxt) : mirC;
;         for (int t = 0; t < nt; t += 2) {
;             const bool last = (t == nt - 2);
;             if constexpr (Epi::MIDK) { if (t == g.ksplit) E.mid(acc, cur, wr, wc, fr, fq); }
;             const char *a1, *a2;
;             if constexpr (SPLITA) {
;                 a1 = (t + 1 < g.ksplit) ? cA + (size_t)(t + 1) * kstep : cA2 + (size_t)(t + 1 - g.ksplit) * 2048;
;                 a2 = last ? nA : ((t + 2 < g.ksplit) ? cA + (size_t)(t + 2) * kstep : cA2 + (size_t)(t + 2 - g.ksplit) * 2048);
;             } else { a1 = cA + kofs(t + 1); a2 = last ? nA : cA + kofs(t + 2); }
;             const char* b2 = last ? nB : cB + (size_t)(t + 2) * kstepB;
;             const bool s2a = SPLITA && (t + 1 >= g.ksplit), s2b = SPLITA && !last && (t + 2 >= g.ksplit);
;             const char* a3 = a2 + ((Epi::KSUB || s2b) ? (size_t)2048 : kstep); const char* b3 = b2 + kstepB;
;             const bool m1 = SPLITA && mirC && (t + 1 < g.ksplit), m2 = SPLITA && (last ? mirN : (mirC && (t + 2 < g.ksplit)));
;             const unsigned vo1[2] = {s2a ? voffA2[0] : m1 ? voffAm[0] : voffA[0], s2a ? voffA2[1] : m1 ? voffAm[1] : voffA[1]}, vo2[2] = {s2b ? voffA2[0] : m2 ? voffAm[0] : voffA[0], s2b ? voffA2[1] : m2 ? voffAm[1] : voffA[1]};
;             const char* a1h = m1 ? a1 - hstepA : a1 + hstepA; const char* a2h = m2 ? a2 - hstepA : a2 + hstepA;
;             PG8_LDB(B0, 0, 0); PG8_LDB(B1, 0, 1); PG8_SCHED; PG8_LDA(At, 0, 0); PG8_STAGE(PG8_SA(1, 1), a1h, vo1);
;             PG8_WAIT_V(8); PG8_WAIT_L(0); PG8_BAR; PG8_MMA(0, 0, At, B0); PG8_MMA(0, 1, At, B1); PG8_BAR; PG8_SCHED;
;             PG8_LDA(At, 0, 1); PG8_STAGE(PG8_SB(0, 0), b2, voffB); PG8_STAGE(PG8_SB(0, 1), b2 + hstepB, voffB); PG8_STAGE(PG8_SA(0, 0), a2, vo2);
;             PG8_WAIT_V(8); PG8_WAIT_L(0); PG8_BAR; PG8_MMA(1, 0, At, B0); PG8_MMA(1, 1, At, B1); PG8_BAR; PG8_SCHED;
.LBB0_708:
	s_ashr_i32 s23, s22, 31
	s_lshl_b64 s[12:13], s[22:23], 19
	s_add_u32 s30, s84, s12
	s_addc_u32 s31, s85, s13
	s_and_b64 s[12:13], s[4:5], exec
	s_cselect_b32 s23, s31, s43
	s_cselect_b32 s39, s30, s42
	s_ashr_i32 s25, s24, 31
	s_lshl_b64 s[12:13], s[24:25], 19
	s_add_u32 s36, s28, s12
	s_addc_u32 s37, s29, s13
	s_and_b64 s[12:13], s[4:5], exec
	s_cselect_b32 s25, s37, s45
	s_cselect_b32 s57, s36, s44
	s_add_u32 s60, s44, 0x100
	s_addc_u32 s61, s45, 0
	s_mov_b32 s44, -2
	s_movk_i32 s64, 0x1000
	s_add_i32 s65, s44, 2
	s_lshr_b32 s8, s65, 2
	s_lshl_b64 s[12:13], s[8:9], 17
	s_add_i32 s8, s64, 0xfffff000
	s_and_b32 s8, s8, 0x1000
	s_add_u32 s12, s42, s12
	s_addc_u32 s13, s43, s13
	s_add_u32 s45, s12, s8
	s_addc_u32 s46, s13, 0
	s_add_i32 s8, s44, 4
	ds_read_b128 v[130:133], v189
	ds_read_b128 v[134:137], v189 offset:1024
	ds_read_b128 v[138:141], v189 offset:2048
	ds_read_b128 v[142:145], v189 offset:3072
	ds_read_b128 v[146:149], v192
	ds_read_b128 v[150:153], v192 offset:1024
	ds_read_b128 v[166:169], v192 offset:2048
	ds_read_b128 v[170:173], v192 offset:3072
	s_lshr_b32 s8, s8, 2
	s_lshl_b64 s[12:13], s[8:9], 17
	s_and_b32 s8, s64, 0x1000
	s_add_u32 s12, s42, s12
	s_addc_u32 s13, s43, s13
	s_add_u32 s8, s12, s8
	s_addc_u32 s47, s13, 0
	s_add_u32 s12, s45, 0x10800
	s_addc_u32 s13, s46, 0
	s_cmp_eq_u32 s44, 12
	s_cselect_b32 s44, s57, s60
	s_cselect_b32 s47, s23, s47
	s_cselect_b32 s46, s39, s8
	s_cselect_b32 s45, s25, s61
	s_add_i32 m0, s7, 0xc000
	ds_read_b128 v[178:181], v193
	ds_read_b128 v[184:187], v193 offset:1024
	ds_read_b128 v[194:197], v193 offset:2048
	ds_read_b128 v[198:201], v193 offset:3072
	ds_read_b128 v[202:205], v193 offset:4096
	ds_read_b128 v[206:209], v193 offset:5120
	ds_read_b128 v[210:213], v193 offset:6144
	ds_read_b128 v[214:217], v193 offset:7168
	global_load_lds_dwordx4 v154, s[12:13]
	s_add_i32 m0, s7, 0xe000
	s_nop 0
	global_load_lds_dwordx4 v158, s[12:13]
	s_waitcnt vmcnt(8)
	s_waitcnt lgkmcnt(0)
	s_barrier
	s_setprio 1
	s_waitcnt lgkmcnt(0)
	v_mfma_f32_16x16x32_bf16 v[126:129], v[130:133], v[178:181], 0
	v_mfma_f32_16x16x32_bf16 v[122:125], v[138:141], v[178:181], 0
	v_mfma_f32_16x16x32_bf16 v[110:113], v[130:133], v[194:197], 0
	v_mfma_f32_16x16x32_bf16 v[106:109], v[138:141], v[194:197], 0
	v_mfma_f32_16x16x32_bf16 v[94:97], v[130:133], v[202:205], 0
	v_mfma_f32_16x16x32_bf16 v[90:93], v[138:141], v[202:205], 0
	v_mfma_f32_16x16x32_bf16 v[78:81], v[130:133], v[210:213], 0
	v_mfma_f32_16x16x32_bf16 v[74:77], v[138:141], v[210:213], 0
	v_mfma_f32_16x16x32_bf16 v[126:129], v[134:137], v[184:187], v[126:129]
	v_mfma_f32_16x16x32_bf16 v[122:125], v[142:145], v[184:187], v[122:125]
	v_mfma_f32_16x16x32_bf16 v[110:113], v[134:137], v[198:201], v[110:113]
	v_mfma_f32_16x16x32_bf16 v[106:109], v[142:145], v[198:201], v[106:109]
	v_mfma_f32_16x16x32_bf16 v[94:97], v[134:137], v[206:209], v[94:97]
	v_mfma_f32_16x16x32_bf16 v[90:93], v[142:145], v[206:209], v[90:93]
	v_mfma_f32_16x16x32_bf16 v[78:81], v[134:137], v[214:217], v[78:81]
	v_mfma_f32_16x16x32_bf16 v[74:77], v[142:145], v[214:217], v[74:77]
	s_setprio 0
	s_setprio 1
	v_mfma_f32_16x16x32_bf16 v[118:121], v[146:149], v[178:181], 0
	v_mfma_f32_16x16x32_bf16 v[114:117], v[166:169], v[178:181], 0
	v_mfma_f32_16x16x32_bf16 v[102:105], v[146:149], v[194:197], 0
	v_mfma_f32_16x16x32_bf16 v[98:101], v[166:169], v[194:197], 0
	v_mfma_f32_16x16x32_bf16 v[86:89], v[146:149], v[202:205], 0
	v_mfma_f32_16x16x32_bf16 v[82:85], v[166:169], v[202:205], 0
	v_mfma_f32_16x16x32_bf16 v[70:73], v[146:149], v[210:213], 0
	v_mfma_f32_16x16x32_bf16 v[66:69], v[166:169], v[210:213], 0
	v_mfma_f32_16x16x32_bf16 v[118:121], v[150:153], v[184:187], v[118:121]
	v_mfma_f32_16x16x32_bf16 v[114:117], v[170:173], v[184:187], v[114:117]
	v_mfma_f32_16x16x32_bf16 v[102:105], v[150:153], v[198:201], v[102:105]
	v_mfma_f32_16x16x32_bf16 v[98:101], v[170:173], v[198:201], v[98:101]
	v_mfma_f32_16x16x32_bf16 v[86:89], v[150:153], v[206:209], v[86:89]
	v_mfma_f32_16x16x32_bf16 v[82:85], v[170:173], v[206:209], v[82:85]
	v_mfma_f32_16x16x32_bf16 v[70:73], v[150:153], v[214:217], v[70:73]
	v_mfma_f32_16x16x32_bf16 v[66:69], v[170:173], v[214:217], v[66:69]
	s_setprio 0
	s_barrier
	s_add_u32 s98, s44, s16
	s_addc_u32 s99, s45, s17
	s_add_u32 s100, s46, s18
	s_addc_u32 s101, s47, s19
	s_add_i32 s8, s54, s6
	s_mov_b32 m0, s8
	ds_read_b128 v[178:181], v193 offset:16384
	ds_read_b128 v[184:187], v193 offset:17408
	ds_read_b128 v[194:197], v193 offset:18432
	ds_read_b128 v[198:201], v193 offset:19456
	ds_read_b128 v[202:205], v193 offset:20480
	ds_read_b128 v[206:209], v193 offset:21504
	ds_read_b128 v[210:213], v193 offset:22528
	ds_read_b128 v[214:217], v193 offset:23552
	global_load_lds_dwordx4 v156, s[44:45]
	s_add_i32 m0, s8, 0x2000
	s_add_u32 s12, s44, 0x40000
	s_addc_u32 s13, s45, 0
	s_add_i32 s8, s55, s6
	global_load_lds_dwordx4 v160, s[44:45]
	s_mov_b32 m0, s8
	s_nop 0
	global_load_lds_dwordx4 v156, s[12:13]
	s_add_i32 m0, s8, 0x2000
	s_nop 0
	global_load_lds_dwordx4 v160, s[12:13]
	s_mov_b32 m0, s7
	s_nop 0
	global_load_lds_dwordx4 v154, s[46:47]
	s_mov_b32 m0, s33
	s_nop 0
	global_load_lds_dwordx4 v158, s[46:47]
	s_waitcnt vmcnt(8)
	s_waitcnt lgkmcnt(0)
	s_barrier
; #define PG8_STAGE(bufoff, gbase, voff) do { _Pragma("unroll") for (int _i = 0; _i < 2; ++_i) \
;         __builtin_amdgcn_global_load_lds((const unsigned*)((const char*)(gbase) + (voff)[_i]), (LAS unsigned*)(lds + (bufoff) + ldsw + _i * 8192), 16, 0, 0); } while (0)
; #define PG8_LDA(dst, b, h) do { _Pragma("unroll") for (int m = 0; m < 4; ++m) _Pragma("unroll") for (int k = 0; k < 2; ++k) dst[m][k] = *(const LAS bf16x8*)(lds + PG8_SA(b, h) + aoff + m * 2048 + k * 1024); } while (0)
; #define PG8_LDB(dst, b, h) do { _Pragma("unroll") for (int n = 0; n < 2; ++n) _Pragma("unroll") for (int k = 0; k < 2; ++k) dst[n][k] = *(const LAS bf16x8*)(lds + PG8_SB(b, h) + boff + n * 2048 + k * 1024); } while (0)
; #define PG8_MMA(ai, bj, At, Bt) do { __builtin_amdgcn_s_setprio(1); _Pragma("unroll") for (int m = 0; m < 4; ++m) _Pragma("unroll") for (int n = 0; n < 2; ++n) _Pragma("unroll") for (int k = 0; k < 2; ++k) \
;         acc[ai][bj][m][n] = __builtin_amdgcn_mfma_f32_16x16x32_bf16(Bt[n][k], At[m][k], acc[ai][bj][m][n], 0, 0, 0); __builtin_amdgcn_s_setprio(0); } while (0)
; #define PG8_WAIT_V(n) asm volatile("s_waitcnt vmcnt(" #n ")" ::: "memory")
; #define PG8_WAIT_L(n) asm volatile("s_waitcnt lgkmcnt(" #n ")" ::: "memory")
; #define PG8_BAR __builtin_amdgcn_s_barrier()
; #define PG8_SCHED __builtin_amdgcn_sched_barrier(0)
; template <class Epi, bool ALIGN_EPI, bool SPLITA>
; __device__ __forceinline__ void gemm_phase(LAS unsigned char* lds, const Gemm g, const StaticOrder& S, const Epi& E) {
;     ...
;             PG8_WAIT_V(8); PG8_WAIT_L(0); PG8_BAR; PG8_MMA(1, 0, At, B0); PG8_MMA(1, 1, At, B1); PG8_BAR; PG8_SCHED;
;             PG8_LDB(B0, 1, 0); PG8_LDB(B1, 1, 1); PG8_SCHED; PG8_LDA(At, 1, 0); PG8_STAGE(PG8_SA(0, 1), a2h, vo2);
;             PG8_WAIT_V(8); PG8_WAIT_L(0); PG8_BAR; PG8_MMA(0, 0, At, B0); PG8_MMA(0, 1, At, B1); PG8_BAR; PG8_SCHED;
	s_setprio 1
	s_waitcnt lgkmcnt(0)
	v_mfma_f32_16x16x32_bf16 v[62:65], v[130:133], v[178:181], 0
	v_mfma_f32_16x16x32_bf16 v[58:61], v[138:141], v[178:181], 0
	v_mfma_f32_16x16x32_bf16 v[38:41], v[130:133], v[194:197], 0
	v_mfma_f32_16x16x32_bf16 v[34:37], v[138:141], v[194:197], 0
	v_mfma_f32_16x16x32_bf16 v[22:25], v[130:133], v[202:205], 0
	v_mfma_f32_16x16x32_bf16 v[18:21], v[138:141], v[202:205], 0
	v_mfma_f32_16x16x32_bf16 v[6:9], v[130:133], v[210:213], 0
	v_mfma_f32_16x16x32_bf16 v[2:5], v[138:141], v[210:213], 0
	v_mfma_f32_16x16x32_bf16 v[62:65], v[134:137], v[184:187], v[62:65]
	v_mfma_f32_16x16x32_bf16 v[58:61], v[142:145], v[184:187], v[58:61]
	v_mfma_f32_16x16x32_bf16 v[38:41], v[134:137], v[198:201], v[38:41]
	v_mfma_f32_16x16x32_bf16 v[34:37], v[142:145], v[198:201], v[34:37]
	v_mfma_f32_16x16x32_bf16 v[22:25], v[134:137], v[206:209], v[22:25]
	v_mfma_f32_16x16x32_bf16 v[18:21], v[142:145], v[206:209], v[18:21]
	v_mfma_f32_16x16x32_bf16 v[6:9], v[134:137], v[214:217], v[6:9]
	v_mfma_f32_16x16x32_bf16 v[2:5], v[142:145], v[214:217], v[2:5]
	s_setprio 0
	s_setprio 1
	v_mfma_f32_16x16x32_bf16 v[54:57], v[146:149], v[178:181], 0
	v_mfma_f32_16x16x32_bf16 v[46:49], v[166:169], v[178:181], 0
	v_mfma_f32_16x16x32_bf16 v[50:53], v[146:149], v[194:197], 0
	v_mfma_f32_16x16x32_bf16 v[42:45], v[166:169], v[194:197], 0
	v_mfma_f32_16x16x32_bf16 v[30:33], v[146:149], v[202:205], 0
	v_mfma_f32_16x16x32_bf16 v[26:29], v[166:169], v[202:205], 0
	v_mfma_f32_16x16x32_bf16 v[14:17], v[146:149], v[210:213], 0
	v_mfma_f32_16x16x32_bf16 v[10:13], v[166:169], v[210:213], 0
	v_mfma_f32_16x16x32_bf16 v[54:57], v[150:153], v[184:187], v[54:57]
	v_mfma_f32_16x16x32_bf16 v[46:49], v[170:173], v[184:187], v[46:49]
	v_mfma_f32_16x16x32_bf16 v[50:53], v[150:153], v[198:201], v[50:53]
	v_mfma_f32_16x16x32_bf16 v[42:45], v[170:173], v[198:201], v[42:45]
	v_mfma_f32_16x16x32_bf16 v[30:33], v[150:153], v[206:209], v[30:33]
	v_mfma_f32_16x16x32_bf16 v[26:29], v[170:173], v[206:209], v[26:29]
	v_mfma_f32_16x16x32_bf16 v[14:17], v[150:153], v[214:217], v[14:17]
	v_mfma_f32_16x16x32_bf16 v[10:13], v[170:173], v[214:217], v[10:13]
	s_setprio 0
	s_barrier
	s_add_i32 s8, 0, 0x18000
	s_add_i32 s70, 0, 0x1c000
	v_add_u32_e32 v142, s8, v177
	v_add_u32_e32 v170, s70, v177
	ds_read_b128 v[130:133], v142
	ds_read_b128 v[134:137], v142 offset:1024
	ds_read_b128 v[138:141], v142 offset:2048
	ds_read_b128 v[142:145], v142 offset:3072
	ds_read_b128 v[146:149], v170
	ds_read_b128 v[150:153], v170 offset:1024
	ds_read_b128 v[166:169], v170 offset:2048
	ds_read_b128 v[170:173], v170 offset:3072
	s_add_u32 s12, s46, 0x10000
	s_addc_u32 s13, s47, 0
	s_mov_b32 m0, s41
	ds_read_b128 v[178:181], v193 offset:32768
	ds_read_b128 v[184:187], v193 offset:33792
	ds_read_b128 v[194:197], v193 offset:34816
	ds_read_b128 v[198:201], v193 offset:35840
	ds_read_b128 v[202:205], v193 offset:36864
	ds_read_b128 v[206:209], v193 offset:37888
	ds_read_b128 v[210:213], v193 offset:38912
	ds_read_b128 v[214:217], v193 offset:39936
	global_load_lds_dwordx4 v154, s[12:13]
	s_mov_b32 m0, s48
	s_nop 0
	global_load_lds_dwordx4 v158, s[12:13]
	s_waitcnt vmcnt(8)
	s_waitcnt lgkmcnt(0)
	s_barrier
	s_setprio 1
	s_waitcnt lgkmcnt(0)
	v_mfma_f32_16x16x32_bf16 v[126:129], v[130:133], v[178:181], v[126:129]
	v_mfma_f32_16x16x32_bf16 v[122:125], v[138:141], v[178:181], v[122:125]
	v_mfma_f32_16x16x32_bf16 v[110:113], v[130:133], v[194:197], v[110:113]
	v_mfma_f32_16x16x32_bf16 v[106:109], v[138:141], v[194:197], v[106:109]
	v_mfma_f32_16x16x32_bf16 v[94:97], v[130:133], v[202:205], v[94:97]
	v_mfma_f32_16x16x32_bf16 v[90:93], v[138:141], v[202:205], v[90:93]
	v_mfma_f32_16x16x32_bf16 v[78:81], v[130:133], v[210:213], v[78:81]
	v_mfma_f32_16x16x32_bf16 v[74:77], v[138:141], v[210:213], v[74:77]
	v_mfma_f32_16x16x32_bf16 v[126:129], v[134:137], v[184:187], v[126:129]
	v_mfma_f32_16x16x32_bf16 v[122:125], v[142:145], v[184:187], v[122:125]
	v_mfma_f32_16x16x32_bf16 v[110:113], v[134:137], v[198:201], v[110:113]
	v_mfma_f32_16x16x32_bf16 v[106:109], v[142:145], v[198:201], v[106:109]
	v_mfma_f32_16x16x32_bf16 v[94:97], v[134:137], v[206:209], v[94:97]
	v_mfma_f32_16x16x32_bf16 v[90:93], v[142:145], v[206:209], v[90:93]
	v_mfma_f32_16x16x32_bf16 v[78:81], v[134:137], v[214:217], v[78:81]
	v_mfma_f32_16x16x32_bf16 v[74:77], v[142:145], v[214:217], v[74:77]
	s_setprio 0
	s_setprio 1
	v_mfma_f32_16x16x32_bf16 v[118:121], v[146:149], v[178:181], v[118:121]
	v_mfma_f32_16x16x32_bf16 v[114:117], v[166:169], v[178:181], v[114:117]
	v_mfma_f32_16x16x32_bf16 v[102:105], v[146:149], v[194:197], v[102:105]
	v_mfma_f32_16x16x32_bf16 v[98:101], v[166:169], v[194:197], v[98:101]
	v_mfma_f32_16x16x32_bf16 v[86:89], v[146:149], v[202:205], v[86:89]
	v_mfma_f32_16x16x32_bf16 v[82:85], v[166:169], v[202:205], v[82:85]
	v_mfma_f32_16x16x32_bf16 v[70:73], v[146:149], v[210:213], v[70:73]
	v_mfma_f32_16x16x32_bf16 v[66:69], v[166:169], v[210:213], v[66:69]
	v_mfma_f32_16x16x32_bf16 v[118:121], v[150:153], v[184:187], v[118:121]
	v_mfma_f32_16x16x32_bf16 v[114:117], v[170:173], v[184:187], v[114:117]
	v_mfma_f32_16x16x32_bf16 v[102:105], v[150:153], v[198:201], v[102:105]
	v_mfma_f32_16x16x32_bf16 v[98:101], v[170:173], v[198:201], v[98:101]
	v_mfma_f32_16x16x32_bf16 v[86:89], v[150:153], v[206:209], v[86:89]
	v_mfma_f32_16x16x32_bf16 v[82:85], v[170:173], v[206:209], v[82:85]
	v_mfma_f32_16x16x32_bf16 v[70:73], v[150:153], v[214:217], v[70:73]
	v_mfma_f32_16x16x32_bf16 v[66:69], v[170:173], v[214:217], v[66:69]
	s_setprio 0
	s_barrier
; #define PG8_STAGE(bufoff, gbase, voff) do { _Pragma("unroll") for (int _i = 0; _i < 2; ++_i) \
;         __builtin_amdgcn_global_load_lds((const unsigned*)((const char*)(gbase) + (voff)[_i]), (LAS unsigned*)(lds + (bufoff) + ldsw + _i * 8192), 16, 0, 0); } while (0)
; #define PG8_LDA(dst, b, h) do { _Pragma("unroll") for (int m = 0; m < 4; ++m) _Pragma("unroll") for (int k = 0; k < 2; ++k) dst[m][k] = *(const LAS bf16x8*)(lds + PG8_SA(b, h) + aoff + m * 2048 + k * 1024); } while (0)
; #define PG8_MMA(ai, bj, At, Bt) do { __builtin_amdgcn_s_setprio(1); _Pragma("unroll") for (int m = 0; m < 4; ++m) _Pragma("unroll") for (int n = 0; n < 2; ++n) _Pragma("unroll") for (int k = 0; k < 2; ++k) \
;         acc[ai][bj][m][n] = __builtin_amdgcn_mfma_f32_16x16x32_bf16(Bt[n][k], At[m][k], acc[ai][bj][m][n], 0, 0, 0); __builtin_amdgcn_s_setprio(0); } while (0)
; #define PG8_WAIT_V(n) asm volatile("s_waitcnt vmcnt(" #n ")" ::: "memory")
; #define PG8_WAIT_L(n) asm volatile("s_waitcnt lgkmcnt(" #n ")" ::: "memory")
; #define PG8_BAR __builtin_amdgcn_s_barrier()
; #define PG8_SCHED __builtin_amdgcn_sched_barrier(0)
; template <class Epi, bool ALIGN_EPI, bool SPLITA>
; __device__ __forceinline__ void gemm_phase(LAS unsigned char* lds, const Gemm g, const StaticOrder& S, const Epi& E) {
;     ...
;             PG8_LDA(At, 1, 1); PG8_STAGE(PG8_SB(1, 0), b3, voffB); PG8_STAGE(PG8_SB(1, 1), b3 + hstepB, voffB); PG8_STAGE(PG8_SA(1, 0), a3, vo2);
;             PG8_WAIT_V(8); PG8_WAIT_L(0); PG8_BAR; PG8_MMA(1, 0, At, B0); PG8_MMA(1, 1, At, B1); PG8_BAR; PG8_SCHED;
	s_add_i32 s8, s8, s6
	s_mov_b32 m0, s8
	ds_read_b128 v[178:181], v193 offset:49152
	ds_read_b128 v[184:187], v193 offset:50176
	ds_read_b128 v[194:197], v193 offset:51200
	ds_read_b128 v[198:201], v193 offset:52224
	ds_read_b128 v[202:205], v193 offset:53248
	ds_read_b128 v[206:209], v193 offset:54272
	ds_read_b128 v[210:213], v193 offset:55296
	ds_read_b128 v[214:217], v193 offset:56320
	global_load_lds_dwordx4 v156, s[98:99]
	s_add_i32 m0, s8, 0x2000
	s_add_u32 s12, s44, 0x40080
	s_addc_u32 s13, s45, 0
	s_add_i32 s8, s70, s6
	global_load_lds_dwordx4 v160, s[98:99]
	s_mov_b32 m0, s8
	s_nop 0
	global_load_lds_dwordx4 v156, s[12:13]
	s_add_i32 m0, s8, 0x2000
	s_nop 0
	global_load_lds_dwordx4 v160, s[12:13]
	s_mov_b32 m0, s49
	s_nop 0
	global_load_lds_dwordx4 v154, s[100:101]
	s_mov_b32 m0, s50
	s_nop 0
	global_load_lds_dwordx4 v158, s[100:101]
	s_waitcnt vmcnt(8)
	s_waitcnt lgkmcnt(0)
	s_barrier
	s_setprio 1
	s_waitcnt lgkmcnt(0)
	v_mfma_f32_16x16x32_bf16 v[62:65], v[130:133], v[178:181], v[62:65]
	v_mfma_f32_16x16x32_bf16 v[58:61], v[138:141], v[178:181], v[58:61]
	v_mfma_f32_16x16x32_bf16 v[38:41], v[130:133], v[194:197], v[38:41]
	v_mfma_f32_16x16x32_bf16 v[34:37], v[138:141], v[194:197], v[34:37]
	v_mfma_f32_16x16x32_bf16 v[22:25], v[130:133], v[202:205], v[22:25]
	v_mfma_f32_16x16x32_bf16 v[18:21], v[138:141], v[202:205], v[18:21]
	v_mfma_f32_16x16x32_bf16 v[6:9], v[130:133], v[210:213], v[6:9]
	v_mfma_f32_16x16x32_bf16 v[2:5], v[138:141], v[210:213], v[2:5]
	v_mfma_f32_16x16x32_bf16 v[62:65], v[134:137], v[184:187], v[62:65]
	v_mfma_f32_16x16x32_bf16 v[58:61], v[142:145], v[184:187], v[58:61]
	v_mfma_f32_16x16x32_bf16 v[38:41], v[134:137], v[198:201], v[38:41]
	v_mfma_f32_16x16x32_bf16 v[34:37], v[142:145], v[198:201], v[34:37]
	v_mfma_f32_16x16x32_bf16 v[22:25], v[134:137], v[206:209], v[22:25]
	v_mfma_f32_16x16x32_bf16 v[18:21], v[142:145], v[206:209], v[18:21]
	v_mfma_f32_16x16x32_bf16 v[6:9], v[134:137], v[214:217], v[6:9]
	v_mfma_f32_16x16x32_bf16 v[2:5], v[142:145], v[214:217], v[2:5]
	s_setprio 0
	s_setprio 1
	v_mfma_f32_16x16x32_bf16 v[54:57], v[146:149], v[178:181], v[54:57]
	v_mfma_f32_16x16x32_bf16 v[46:49], v[166:169], v[178:181], v[46:49]
	v_mfma_f32_16x16x32_bf16 v[50:53], v[146:149], v[194:197], v[50:53]
	v_mfma_f32_16x16x32_bf16 v[42:45], v[166:169], v[194:197], v[42:45]
	v_mfma_f32_16x16x32_bf16 v[30:33], v[146:149], v[202:205], v[30:33]
	v_mfma_f32_16x16x32_bf16 v[26:29], v[166:169], v[202:205], v[26:29]
	v_mfma_f32_16x16x32_bf16 v[14:17], v[146:149], v[210:213], v[14:17]
	v_mfma_f32_16x16x32_bf16 v[10:13], v[166:169], v[210:213], v[10:13]
	v_mfma_f32_16x16x32_bf16 v[54:57], v[150:153], v[184:187], v[54:57]
	v_mfma_f32_16x16x32_bf16 v[46:49], v[170:173], v[184:187], v[46:49]
	v_mfma_f32_16x16x32_bf16 v[50:53], v[150:153], v[198:201], v[50:53]
	v_mfma_f32_16x16x32_bf16 v[42:45], v[170:173], v[198:201], v[42:45]
	v_mfma_f32_16x16x32_bf16 v[30:33], v[150:153], v[206:209], v[30:33]
	v_mfma_f32_16x16x32_bf16 v[26:29], v[170:173], v[206:209], v[26:29]
	v_mfma_f32_16x16x32_bf16 v[14:17], v[150:153], v[214:217], v[14:17]
	v_mfma_f32_16x16x32_bf16 v[10:13], v[170:173], v[214:217], v[10:13]
	s_setprio 0
	s_barrier
	s_add_u32 s60, s60, 0x100
	s_addc_u32 s61, s61, 0
	s_addk_i32 s64, 0x1000
	s_mov_b32 s44, s65

; #define PG8_WAIT_V(n) asm volatile("s_waitcnt vmcnt(" #n ")" ::: "memory")
; #define PG8_BAR __builtin_amdgcn_s_barrier()
; template <class Epi, bool ALIGN_EPI, bool SPLITA>
; __device__ __forceinline__ void gemm_phase(LAS unsigned char* lds, const Gemm g, const StaticOrder& S, const Epi& E) {
;     ...
;         const bool has_next = S.next(ui + 1, nxt);
;         const char* nA = has_next ? baseA1(nxt) : cA;
;         const char* nB = has_next ? baseB(nxt) : cB;
;         const bool mirN = has_next ? mirrored(nxt) : mirC;
;         for (int t = 0; t < nt; t += 2) {
;             const bool last = (t == nt - 2);
;             if constexpr (Epi::MIDK) { if (t == g.ksplit) E.mid(acc, cur, wr, wc, fr, fq); }
;             const char *a1, *a2;
;             if constexpr (SPLITA) {
;                 a1 = (t + 1 < g.ksplit) ? cA + (size_t)(t + 1) * kstep : cA2 + (size_t)(t + 1 - g.ksplit) * 2048;
;                 a2 = last ? nA : ((t + 2 < g.ksplit) ? cA + (size_t)(t + 2) * kstep : cA2 + (size_t)(t + 2 - g.ksplit) * 2048);
;             } else { a1 = cA + kofs(t + 1); a2 = last ? nA : cA + kofs(t + 2); }
;             const char* b2 = last ? nB : cB + (size_t)(t + 2) * kstepB;
;             const bool s2a = SPLITA && (t + 1 >= g.ksplit), s2b = SPLITA && !last && (t + 2 >= g.ksplit);
;             const char* a3 = a2 + ((Epi::KSUB || s2b) ? (size_t)2048 : kstep); const char* b3 = b2 + kstepB;
;             const bool m1 = SPLITA && mirC && (t + 1 < g.ksplit), m2 = SPLITA && (last ? mirN : (mirC && (t + 2 < g.ksplit)));
;             const unsigned vo1[2] = {s2a ? voffA2[0] : m1 ? voffAm[0] : voffA[0], s2a ? voffA2[1] : m1 ? voffAm[1] : voffA[1]}, vo2[2] = {s2b ? voffA2[0] : m2 ? voffAm[0] : voffA[0], s2b ? voffA2[1] : m2 ? voffAm[1] : voffA[1]};
;             const char* a1h = m1 ? a1 - hstepA : a1 + hstepA; const char* a2h = m2 ? a2 - hstepA : a2 + hstepA;
;             PG8_LDB(B0, 0, 0); PG8_LDB(B1, 0, 1); PG8_SCHED; PG8_LDA(At, 0, 0); PG8_STAGE(PG8_SA(1, 1), a1h, vo1);
;             PG8_WAIT_V(8); PG8_WAIT_L(0); PG8_BAR; PG8_MMA(0, 0, At, B0); PG8_MMA(0, 1, At, B1); PG8_BAR; PG8_SCHED;
;             PG8_LDA(At, 0, 1); PG8_STAGE(PG8_SB(0, 0), b2, voffB); PG8_STAGE(PG8_SB(0, 1), b2 + hstepB, voffB); PG8_STAGE(PG8_SA(0, 0), a2, vo2);
;             PG8_WAIT_V(8); PG8_WAIT_L(0); PG8_BAR; PG8_MMA(1, 0, At, B0); PG8_MMA(1, 1, At, B1); PG8_BAR; PG8_SCHED;
.LBB0_795:
	s_ashr_i32 s19, s18, 31
	s_lshl_b64 s[12:13], s[18:19], 19
	s_add_u32 s22, s34, s12
	s_addc_u32 s23, s35, s13
	s_and_b64 s[12:13], s[2:3], exec
	s_cselect_b32 s19, s23, s39
	s_cselect_b32 s29, s22, s38
	s_ashr_i32 s21, s20, 31
	s_lshl_b64 s[12:13], s[20:21], 19
	s_add_u32 s24, s26, s12
	s_addc_u32 s25, s27, s13
	s_and_b64 s[12:13], s[2:3], exec
	s_cselect_b32 s21, s25, s37
	s_cselect_b32 s31, s24, s36
	s_add_u32 s55, s36, 0x1000
	s_addc_u32 s56, s37, 0
	s_add_u32 s36, s38, 0x40080
	s_addc_u32 s37, s39, 0
	s_mov_b32 s57, -2
	ds_read_b128 v[150:153], v155
	ds_read_b128 v[160:163], v155 offset:1024
	ds_read_b128 v[164:167], v155 offset:2048
	ds_read_b128 v[168:171], v155 offset:3072
	ds_read_b128 v[172:175], v156
	ds_read_b128 v[176:179], v156 offset:1024
	ds_read_b128 v[180:183], v156 offset:2048
	ds_read_b128 v[184:187], v156 offset:3072
	s_add_u32 s12, s36, 0xfffc0080
	s_addc_u32 s13, s37, -1
	s_cmp_eq_u32 s57, 12
	s_cselect_b32 s41, s19, s13
	s_cselect_b32 s40, s29, s12
	s_cselect_b32 s39, s21, s56
	s_cselect_b32 s38, s31, s55
	s_add_i32 m0, s42, 0xc000
	ds_read_b128 v[188:191], v157
	ds_read_b128 v[192:195], v157 offset:1024
	ds_read_b128 v[196:199], v157 offset:2048
	ds_read_b128 v[200:203], v157 offset:3072
	ds_read_b128 v[204:207], v157 offset:4096
	ds_read_b128 v[208:211], v157 offset:5120
	ds_read_b128 v[212:215], v157 offset:6144
	ds_read_b128 v[216:219], v157 offset:7168
	global_load_lds_dwordx4 v140, s[36:37]
	s_add_i32 m0, s42, 0xe000
	s_nop 0
	global_load_lds_dwordx4 v142, s[36:37]
	s_waitcnt vmcnt(8)
	s_waitcnt lgkmcnt(0)
	s_barrier
	s_setprio 1
	s_waitcnt lgkmcnt(0)
	v_mfma_f32_16x16x32_bf16 v[126:129], v[150:153], v[188:191], 0
	v_mfma_f32_16x16x32_bf16 v[122:125], v[164:167], v[188:191], 0
	v_mfma_f32_16x16x32_bf16 v[110:113], v[150:153], v[196:199], 0
	v_mfma_f32_16x16x32_bf16 v[106:109], v[164:167], v[196:199], 0
	v_mfma_f32_16x16x32_bf16 v[94:97], v[150:153], v[204:207], 0
	v_mfma_f32_16x16x32_bf16 v[90:93], v[164:167], v[204:207], 0
	v_mfma_f32_16x16x32_bf16 v[78:81], v[150:153], v[212:215], 0
	v_mfma_f32_16x16x32_bf16 v[74:77], v[164:167], v[212:215], 0
	v_mfma_f32_16x16x32_bf16 v[126:129], v[160:163], v[192:195], v[126:129]
	v_mfma_f32_16x16x32_bf16 v[122:125], v[168:171], v[192:195], v[122:125]
	v_mfma_f32_16x16x32_bf16 v[110:113], v[160:163], v[200:203], v[110:113]
	v_mfma_f32_16x16x32_bf16 v[106:109], v[168:171], v[200:203], v[106:109]
	v_mfma_f32_16x16x32_bf16 v[94:97], v[160:163], v[208:211], v[94:97]
	v_mfma_f32_16x16x32_bf16 v[90:93], v[168:171], v[208:211], v[90:93]
	v_mfma_f32_16x16x32_bf16 v[78:81], v[160:163], v[216:219], v[78:81]
	v_mfma_f32_16x16x32_bf16 v[74:77], v[168:171], v[216:219], v[74:77]
	s_setprio 0
	s_setprio 1
	v_mfma_f32_16x16x32_bf16 v[118:121], v[172:175], v[188:191], 0
	v_mfma_f32_16x16x32_bf16 v[114:117], v[180:183], v[188:191], 0
	v_mfma_f32_16x16x32_bf16 v[102:105], v[172:175], v[196:199], 0
	v_mfma_f32_16x16x32_bf16 v[98:101], v[180:183], v[196:199], 0
	v_mfma_f32_16x16x32_bf16 v[86:89], v[172:175], v[204:207], 0
	v_mfma_f32_16x16x32_bf16 v[82:85], v[180:183], v[204:207], 0
	v_mfma_f32_16x16x32_bf16 v[70:73], v[172:175], v[212:215], 0
	v_mfma_f32_16x16x32_bf16 v[66:69], v[180:183], v[212:215], 0
	v_mfma_f32_16x16x32_bf16 v[118:121], v[176:179], v[192:195], v[118:121]
	v_mfma_f32_16x16x32_bf16 v[114:117], v[184:187], v[192:195], v[114:117]
	v_mfma_f32_16x16x32_bf16 v[102:105], v[176:179], v[200:203], v[102:105]
	v_mfma_f32_16x16x32_bf16 v[98:101], v[184:187], v[200:203], v[98:101]
	v_mfma_f32_16x16x32_bf16 v[86:89], v[176:179], v[208:211], v[86:89]
	v_mfma_f32_16x16x32_bf16 v[82:85], v[184:187], v[208:211], v[82:85]
	v_mfma_f32_16x16x32_bf16 v[70:73], v[176:179], v[216:219], v[70:73]
	v_mfma_f32_16x16x32_bf16 v[66:69], v[184:187], v[216:219], v[66:69]
	s_setprio 0
	s_barrier
	s_add_u32 s98, s38, s8
	s_addc_u32 s99, s39, s9
	s_add_u32 s100, s40, s10
	s_addc_u32 s101, s41, s11
	s_add_i32 s12, s51, s6
	s_mov_b32 m0, s12
	ds_read_b128 v[188:191], v157 offset:16384
	ds_read_b128 v[192:195], v157 offset:17408
	ds_read_b128 v[196:199], v157 offset:18432
	ds_read_b128 v[200:203], v157 offset:19456
	ds_read_b128 v[204:207], v157 offset:20480
	ds_read_b128 v[208:211], v157 offset:21504
	ds_read_b128 v[212:215], v157 offset:22528
	ds_read_b128 v[216:219], v157 offset:23552
	global_load_lds_dwordx4 v134, s[38:39]
	s_add_i32 m0, s12, 0x2000
	s_add_u32 s12, s38, 0x40000
	s_addc_u32 s13, s39, 0
	s_add_i32 s60, s52, s6
	global_load_lds_dwordx4 v130, s[38:39]
	s_mov_b32 m0, s60
	s_nop 0
	global_load_lds_dwordx4 v134, s[12:13]
	s_add_i32 m0, s60, 0x2000
	s_nop 0
	global_load_lds_dwordx4 v130, s[12:13]
	s_mov_b32 m0, s42
	s_nop 0
	global_load_lds_dwordx4 v136, s[40:41]
	s_mov_b32 m0, s43
	s_nop 0
	global_load_lds_dwordx4 v132, s[40:41]
	s_waitcnt vmcnt(8)
	s_waitcnt lgkmcnt(0)
	s_barrier
; #define PG8_STAGE(bufoff, gbase, voff) do { _Pragma("unroll") for (int _i = 0; _i < 2; ++_i) \
;         __builtin_amdgcn_global_load_lds((const unsigned*)((const char*)(gbase) + (voff)[_i]), (LAS unsigned*)(lds + (bufoff) + ldsw + _i * 8192), 16, 0, 0); } while (0)
; #define PG8_LDA(dst, b, h) do { _Pragma("unroll") for (int m = 0; m < 4; ++m) _Pragma("unroll") for (int k = 0; k < 2; ++k) dst[m][k] = *(const LAS bf16x8*)(lds + PG8_SA(b, h) + aoff + m * 2048 + k * 1024); } while (0)
; #define PG8_LDB(dst, b, h) do { _Pragma("unroll") for (int n = 0; n < 2; ++n) _Pragma("unroll") for (int k = 0; k < 2; ++k) dst[n][k] = *(const LAS bf16x8*)(lds + PG8_SB(b, h) + boff + n * 2048 + k * 1024); } while (0)
; #define PG8_MMA(ai, bj, At, Bt) do { __builtin_amdgcn_s_setprio(1); _Pragma("unroll") for (int m = 0; m < 4; ++m) _Pragma("unroll") for (int n = 0; n < 2; ++n) _Pragma("unroll") for (int k = 0; k < 2; ++k) \
;         acc[ai][bj][m][n] = __builtin_amdgcn_mfma_f32_16x16x32_bf16(Bt[n][k], At[m][k], acc[ai][bj][m][n], 0, 0, 0); __builtin_amdgcn_s_setprio(0); } while (0)
; #define PG8_WAIT_V(n) asm volatile("s_waitcnt vmcnt(" #n ")" ::: "memory")
; #define PG8_WAIT_L(n) asm volatile("s_waitcnt lgkmcnt(" #n ")" ::: "memory")
; #define PG8_BAR __builtin_amdgcn_s_barrier()
; #define PG8_SCHED __builtin_amdgcn_sched_barrier(0)
; template <class Epi, bool ALIGN_EPI, bool SPLITA>
; __device__ __forceinline__ void gemm_phase(LAS unsigned char* lds, const Gemm g, const StaticOrder& S, const Epi& E) {
;     ...
;             PG8_WAIT_V(8); PG8_WAIT_L(0); PG8_BAR; PG8_MMA(1, 0, At, B0); PG8_MMA(1, 1, At, B1); PG8_BAR; PG8_SCHED;
;             PG8_LDB(B0, 1, 0); PG8_LDB(B1, 1, 1); PG8_SCHED; PG8_LDA(At, 1, 0); PG8_STAGE(PG8_SA(0, 1), a2h, vo2);
;             PG8_WAIT_V(8); PG8_WAIT_L(0); PG8_BAR; PG8_MMA(0, 0, At, B0); PG8_MMA(0, 1, At, B1); PG8_BAR; PG8_SCHED;
	s_setprio 1
	s_waitcnt lgkmcnt(0)
	v_mfma_f32_16x16x32_bf16 v[62:65], v[150:153], v[188:191], 0
	v_mfma_f32_16x16x32_bf16 v[58:61], v[164:167], v[188:191], 0
	v_mfma_f32_16x16x32_bf16 v[38:41], v[150:153], v[196:199], 0
	v_mfma_f32_16x16x32_bf16 v[34:37], v[164:167], v[196:199], 0
	v_mfma_f32_16x16x32_bf16 v[22:25], v[150:153], v[204:207], 0
	v_mfma_f32_16x16x32_bf16 v[18:21], v[164:167], v[204:207], 0
	v_mfma_f32_16x16x32_bf16 v[6:9], v[150:153], v[212:215], 0
	v_mfma_f32_16x16x32_bf16 v[2:5], v[164:167], v[212:215], 0
	v_mfma_f32_16x16x32_bf16 v[62:65], v[160:163], v[192:195], v[62:65]
	v_mfma_f32_16x16x32_bf16 v[58:61], v[168:171], v[192:195], v[58:61]
	v_mfma_f32_16x16x32_bf16 v[38:41], v[160:163], v[200:203], v[38:41]
	v_mfma_f32_16x16x32_bf16 v[34:37], v[168:171], v[200:203], v[34:37]
	v_mfma_f32_16x16x32_bf16 v[22:25], v[160:163], v[208:211], v[22:25]
	v_mfma_f32_16x16x32_bf16 v[18:21], v[168:171], v[208:211], v[18:21]
	v_mfma_f32_16x16x32_bf16 v[6:9], v[160:163], v[216:219], v[6:9]
	v_mfma_f32_16x16x32_bf16 v[2:5], v[168:171], v[216:219], v[2:5]
	s_setprio 0
	s_setprio 1
	v_mfma_f32_16x16x32_bf16 v[54:57], v[172:175], v[188:191], 0
	v_mfma_f32_16x16x32_bf16 v[50:53], v[180:183], v[188:191], 0
	v_mfma_f32_16x16x32_bf16 v[42:45], v[172:175], v[196:199], 0
	v_mfma_f32_16x16x32_bf16 v[46:49], v[180:183], v[196:199], 0
	v_mfma_f32_16x16x32_bf16 v[26:29], v[172:175], v[204:207], 0
	v_mfma_f32_16x16x32_bf16 v[30:33], v[180:183], v[204:207], 0
	v_mfma_f32_16x16x32_bf16 v[10:13], v[172:175], v[212:215], 0
	v_mfma_f32_16x16x32_bf16 v[14:17], v[180:183], v[212:215], 0
	v_mfma_f32_16x16x32_bf16 v[54:57], v[176:179], v[192:195], v[54:57]
	v_mfma_f32_16x16x32_bf16 v[50:53], v[184:187], v[192:195], v[50:53]
	v_mfma_f32_16x16x32_bf16 v[42:45], v[176:179], v[200:203], v[42:45]
	v_mfma_f32_16x16x32_bf16 v[46:49], v[184:187], v[200:203], v[46:49]
	v_mfma_f32_16x16x32_bf16 v[26:29], v[176:179], v[208:211], v[26:29]
	v_mfma_f32_16x16x32_bf16 v[30:33], v[184:187], v[208:211], v[30:33]
	v_mfma_f32_16x16x32_bf16 v[10:13], v[176:179], v[216:219], v[10:13]
	v_mfma_f32_16x16x32_bf16 v[14:17], v[184:187], v[216:219], v[14:17]
	s_setprio 0
	s_barrier
	s_add_i32 s60, 0, 0x18000
	v_add_u32_e32 v149, s60, v154
	s_add_i32 s61, 0, 0x1c000
	ds_read_b128 v[150:153], v149
	ds_read_b128 v[160:163], v149 offset:1024
	ds_read_b128 v[164:167], v149 offset:2048
	ds_read_b128 v[168:171], v149 offset:3072
	v_add_u32_e32 v149, s61, v154
	ds_read_b128 v[172:175], v149
	ds_read_b128 v[176:179], v149 offset:1024
	ds_read_b128 v[180:183], v149 offset:2048
	ds_read_b128 v[184:187], v149 offset:3072
	s_add_u32 s12, s40, 0x40000
	s_addc_u32 s13, s41, 0
	s_mov_b32 m0, s44
	ds_read_b128 v[188:191], v157 offset:32768
	ds_read_b128 v[192:195], v157 offset:33792
	ds_read_b128 v[196:199], v157 offset:34816
	ds_read_b128 v[200:203], v157 offset:35840
	ds_read_b128 v[204:207], v157 offset:36864
	ds_read_b128 v[208:211], v157 offset:37888
	ds_read_b128 v[212:215], v157 offset:38912
	ds_read_b128 v[216:219], v157 offset:39936
	global_load_lds_dwordx4 v136, s[12:13]
	s_mov_b32 m0, s45
	s_nop 0
	global_load_lds_dwordx4 v132, s[12:13]
	s_waitcnt vmcnt(8)
	s_waitcnt lgkmcnt(0)
	s_barrier
	s_setprio 1
	s_waitcnt lgkmcnt(0)
	v_mfma_f32_16x16x32_bf16 v[126:129], v[150:153], v[188:191], v[126:129]
	v_mfma_f32_16x16x32_bf16 v[122:125], v[164:167], v[188:191], v[122:125]
	v_mfma_f32_16x16x32_bf16 v[110:113], v[150:153], v[196:199], v[110:113]
	v_mfma_f32_16x16x32_bf16 v[106:109], v[164:167], v[196:199], v[106:109]
	v_mfma_f32_16x16x32_bf16 v[94:97], v[150:153], v[204:207], v[94:97]
	v_mfma_f32_16x16x32_bf16 v[90:93], v[164:167], v[204:207], v[90:93]
	v_mfma_f32_16x16x32_bf16 v[78:81], v[150:153], v[212:215], v[78:81]
	v_mfma_f32_16x16x32_bf16 v[74:77], v[164:167], v[212:215], v[74:77]
	v_mfma_f32_16x16x32_bf16 v[126:129], v[160:163], v[192:195], v[126:129]
	v_mfma_f32_16x16x32_bf16 v[122:125], v[168:171], v[192:195], v[122:125]
	v_mfma_f32_16x16x32_bf16 v[110:113], v[160:163], v[200:203], v[110:113]
	v_mfma_f32_16x16x32_bf16 v[106:109], v[168:171], v[200:203], v[106:109]
	v_mfma_f32_16x16x32_bf16 v[94:97], v[160:163], v[208:211], v[94:97]
	v_mfma_f32_16x16x32_bf16 v[90:93], v[168:171], v[208:211], v[90:93]
	v_mfma_f32_16x16x32_bf16 v[78:81], v[160:163], v[216:219], v[78:81]
	v_mfma_f32_16x16x32_bf16 v[74:77], v[168:171], v[216:219], v[74:77]
	s_setprio 0
	s_setprio 1
	v_mfma_f32_16x16x32_bf16 v[118:121], v[172:175], v[188:191], v[118:121]
	v_mfma_f32_16x16x32_bf16 v[114:117], v[180:183], v[188:191], v[114:117]
	v_mfma_f32_16x16x32_bf16 v[102:105], v[172:175], v[196:199], v[102:105]
	v_mfma_f32_16x16x32_bf16 v[98:101], v[180:183], v[196:199], v[98:101]
	v_mfma_f32_16x16x32_bf16 v[86:89], v[172:175], v[204:207], v[86:89]
	v_mfma_f32_16x16x32_bf16 v[82:85], v[180:183], v[204:207], v[82:85]
	v_mfma_f32_16x16x32_bf16 v[70:73], v[172:175], v[212:215], v[70:73]
	v_mfma_f32_16x16x32_bf16 v[66:69], v[180:183], v[212:215], v[66:69]
	v_mfma_f32_16x16x32_bf16 v[118:121], v[176:179], v[192:195], v[118:121]
	v_mfma_f32_16x16x32_bf16 v[114:117], v[184:187], v[192:195], v[114:117]
	v_mfma_f32_16x16x32_bf16 v[102:105], v[176:179], v[200:203], v[102:105]
	v_mfma_f32_16x16x32_bf16 v[98:101], v[184:187], v[200:203], v[98:101]
	v_mfma_f32_16x16x32_bf16 v[86:89], v[176:179], v[208:211], v[86:89]
	v_mfma_f32_16x16x32_bf16 v[82:85], v[184:187], v[208:211], v[82:85]
	v_mfma_f32_16x16x32_bf16 v[70:73], v[176:179], v[216:219], v[70:73]
	v_mfma_f32_16x16x32_bf16 v[66:69], v[184:187], v[216:219], v[66:69]
	s_setprio 0
	s_barrier
; #define PG8_STAGE(bufoff, gbase, voff) do { _Pragma("unroll") for (int _i = 0; _i < 2; ++_i) \
;         __builtin_amdgcn_global_load_lds((const unsigned*)((const char*)(gbase) + (voff)[_i]), (LAS unsigned*)(lds + (bufoff) + ldsw + _i * 8192), 16, 0, 0); } while (0)
; #define PG8_LDA(dst, b, h) do { _Pragma("unroll") for (int m = 0; m < 4; ++m) _Pragma("unroll") for (int k = 0; k < 2; ++k) dst[m][k] = *(const LAS bf16x8*)(lds + PG8_SA(b, h) + aoff + m * 2048 + k * 1024); } while (0)
; #define PG8_MMA(ai, bj, At, Bt) do { __builtin_amdgcn_s_setprio(1); _Pragma("unroll") for (int m = 0; m < 4; ++m) _Pragma("unroll") for (int n = 0; n < 2; ++n) _Pragma("unroll") for (int k = 0; k < 2; ++k) \
;         acc[ai][bj][m][n] = __builtin_amdgcn_mfma_f32_16x16x32_bf16(Bt[n][k], At[m][k], acc[ai][bj][m][n], 0, 0, 0); __builtin_amdgcn_s_setprio(0); } while (0)
; #define PG8_WAIT_V(n) asm volatile("s_waitcnt vmcnt(" #n ")" ::: "memory")
; #define PG8_WAIT_L(n) asm volatile("s_waitcnt lgkmcnt(" #n ")" ::: "memory")
; #define PG8_BAR __builtin_amdgcn_s_barrier()
; #define PG8_SCHED __builtin_amdgcn_sched_barrier(0)
; template <class Epi, bool ALIGN_EPI, bool SPLITA>
; __device__ __forceinline__ void gemm_phase(LAS unsigned char* lds, const Gemm g, const StaticOrder& S, const Epi& E) {
;     ...
;             PG8_LDA(At, 1, 1); PG8_STAGE(PG8_SB(1, 0), b3, voffB); PG8_STAGE(PG8_SB(1, 1), b3 + hstepB, voffB); PG8_STAGE(PG8_SA(1, 0), a3, vo2);
;             PG8_WAIT_V(8); PG8_WAIT_L(0); PG8_BAR; PG8_MMA(1, 0, At, B0); PG8_MMA(1, 1, At, B1); PG8_BAR; PG8_SCHED;
	s_add_i32 s12, s60, s6
	s_mov_b32 m0, s12
	ds_read_b128 v[188:191], v157 offset:49152
	ds_read_b128 v[192:195], v157 offset:50176
	ds_read_b128 v[196:199], v157 offset:51200
	ds_read_b128 v[200:203], v157 offset:52224
	ds_read_b128 v[204:207], v157 offset:53248
	ds_read_b128 v[208:211], v157 offset:54272
	ds_read_b128 v[212:215], v157 offset:55296
	ds_read_b128 v[216:219], v157 offset:56320
	global_load_lds_dwordx4 v134, s[98:99]
	s_add_i32 m0, s12, 0x2000
	s_add_u32 s12, s38, 0x40800
	s_addc_u32 s13, s39, 0
	s_add_i32 s38, s61, s6
	global_load_lds_dwordx4 v130, s[98:99]
	s_mov_b32 m0, s38
	s_nop 0
	global_load_lds_dwordx4 v134, s[12:13]
	s_add_i32 m0, s38, 0x2000
	s_nop 0
	global_load_lds_dwordx4 v130, s[12:13]
	s_mov_b32 m0, s49
	s_nop 0
	global_load_lds_dwordx4 v136, s[100:101]
	s_mov_b32 m0, s50
	s_nop 0
	global_load_lds_dwordx4 v132, s[100:101]
	s_waitcnt vmcnt(8)
	s_waitcnt lgkmcnt(0)
	s_barrier
	s_setprio 1
	s_waitcnt lgkmcnt(0)
	v_mfma_f32_16x16x32_bf16 v[62:65], v[150:153], v[188:191], v[62:65]
	v_mfma_f32_16x16x32_bf16 v[58:61], v[164:167], v[188:191], v[58:61]
	v_mfma_f32_16x16x32_bf16 v[38:41], v[150:153], v[196:199], v[38:41]
	v_mfma_f32_16x16x32_bf16 v[34:37], v[164:167], v[196:199], v[34:37]
	v_mfma_f32_16x16x32_bf16 v[22:25], v[150:153], v[204:207], v[22:25]
	v_mfma_f32_16x16x32_bf16 v[18:21], v[164:167], v[204:207], v[18:21]
	v_mfma_f32_16x16x32_bf16 v[6:9], v[150:153], v[212:215], v[6:9]
	v_mfma_f32_16x16x32_bf16 v[2:5], v[164:167], v[212:215], v[2:5]
	v_mfma_f32_16x16x32_bf16 v[62:65], v[160:163], v[192:195], v[62:65]
	v_mfma_f32_16x16x32_bf16 v[58:61], v[168:171], v[192:195], v[58:61]
	v_mfma_f32_16x16x32_bf16 v[38:41], v[160:163], v[200:203], v[38:41]
	v_mfma_f32_16x16x32_bf16 v[34:37], v[168:171], v[200:203], v[34:37]
	v_mfma_f32_16x16x32_bf16 v[22:25], v[160:163], v[208:211], v[22:25]
	v_mfma_f32_16x16x32_bf16 v[18:21], v[168:171], v[208:211], v[18:21]
	v_mfma_f32_16x16x32_bf16 v[6:9], v[160:163], v[216:219], v[6:9]
	v_mfma_f32_16x16x32_bf16 v[2:5], v[168:171], v[216:219], v[2:5]
	s_setprio 0
	s_setprio 1
	v_mfma_f32_16x16x32_bf16 v[54:57], v[172:175], v[188:191], v[54:57]
	v_mfma_f32_16x16x32_bf16 v[50:53], v[180:183], v[188:191], v[50:53]
	v_mfma_f32_16x16x32_bf16 v[42:45], v[172:175], v[196:199], v[42:45]
	v_mfma_f32_16x16x32_bf16 v[46:49], v[180:183], v[196:199], v[46:49]
	v_mfma_f32_16x16x32_bf16 v[26:29], v[172:175], v[204:207], v[26:29]
	v_mfma_f32_16x16x32_bf16 v[30:33], v[180:183], v[204:207], v[30:33]
	v_mfma_f32_16x16x32_bf16 v[10:13], v[172:175], v[212:215], v[10:13]
	v_mfma_f32_16x16x32_bf16 v[14:17], v[180:183], v[212:215], v[14:17]
	v_mfma_f32_16x16x32_bf16 v[54:57], v[176:179], v[192:195], v[54:57]
	v_mfma_f32_16x16x32_bf16 v[50:53], v[184:187], v[192:195], v[50:53]
	v_mfma_f32_16x16x32_bf16 v[42:45], v[176:179], v[200:203], v[42:45]
	v_mfma_f32_16x16x32_bf16 v[46:49], v[184:187], v[200:203], v[46:49]
	v_mfma_f32_16x16x32_bf16 v[26:29], v[176:179], v[208:211], v[26:29]
	v_mfma_f32_16x16x32_bf16 v[30:33], v[184:187], v[208:211], v[30:33]
	v_mfma_f32_16x16x32_bf16 v[10:13], v[176:179], v[216:219], v[10:13]
	v_mfma_f32_16x16x32_bf16 v[14:17], v[184:187], v[216:219], v[14:17]
	s_setprio 0
	s_barrier
	s_add_i32 s57, s57, 2
	s_add_u32 s55, s55, 0x1000
	s_addc_u32 s56, s56, 0
	s_add_u32 s36, s36, 0x100
	s_addc_u32 s37, s37, 0

; #define PG8_WAIT_V(n) asm volatile("s_waitcnt vmcnt(" #n ")" ::: "memory")
; #define PG8_BAR __builtin_amdgcn_s_barrier()
; template <class Epi, bool ALIGN_EPI, bool SPLITA>
; __device__ __forceinline__ void gemm_phase(LAS unsigned char* lds, const Gemm g, const StaticOrder& S, const Epi& E) {
;     ...
;         const bool has_next = S.next(ui + 1, nxt);
;         const char* nA = has_next ? baseA1(nxt) : cA;
;         const char* nB = has_next ? baseB(nxt) : cB;
;         const bool mirN = has_next ? mirrored(nxt) : mirC;
;         for (int t = 0; t < nt; t += 2) {
;             const bool last = (t == nt - 2);
;             if constexpr (Epi::MIDK) { if (t == g.ksplit) E.mid(acc, cur, wr, wc, fr, fq); }
;             const char *a1, *a2;
;             if constexpr (SPLITA) {
;                 a1 = (t + 1 < g.ksplit) ? cA + (size_t)(t + 1) * kstep : cA2 + (size_t)(t + 1 - g.ksplit) * 2048;
;                 a2 = last ? nA : ((t + 2 < g.ksplit) ? cA + (size_t)(t + 2) * kstep : cA2 + (size_t)(t + 2 - g.ksplit) * 2048);
;             } else { a1 = cA + kofs(t + 1); a2 = last ? nA : cA + kofs(t + 2); }
;             const char* b2 = last ? nB : cB + (size_t)(t + 2) * kstepB;
;             const bool s2a = SPLITA && (t + 1 >= g.ksplit), s2b = SPLITA && !last && (t + 2 >= g.ksplit);
;             const char* a3 = a2 + ((Epi::KSUB || s2b) ? (size_t)2048 : kstep); const char* b3 = b2 + kstepB;
;             const bool m1 = SPLITA && mirC && (t + 1 < g.ksplit), m2 = SPLITA && (last ? mirN : (mirC && (t + 2 < g.ksplit)));
;             const unsigned vo1[2] = {s2a ? voffA2[0] : m1 ? voffAm[0] : voffA[0], s2a ? voffA2[1] : m1 ? voffAm[1] : voffA[1]}, vo2[2] = {s2b ? voffA2[0] : m2 ? voffAm[0] : voffA[0], s2b ? voffA2[1] : m2 ? voffAm[1] : voffA[1]};
;             const char* a1h = m1 ? a1 - hstepA : a1 + hstepA; const char* a2h = m2 ? a2 - hstepA : a2 + hstepA;
;             PG8_LDB(B0, 0, 0); PG8_LDB(B1, 0, 1); PG8_SCHED; PG8_LDA(At, 0, 0); PG8_STAGE(PG8_SA(1, 1), a1h, vo1);
;             PG8_WAIT_V(8); PG8_WAIT_L(0); PG8_BAR; PG8_MMA(0, 0, At, B0); PG8_MMA(0, 1, At, B1); PG8_BAR; PG8_SCHED;
;             PG8_LDA(At, 0, 1); PG8_STAGE(PG8_SB(0, 0), b2, voffB); PG8_STAGE(PG8_SB(0, 1), b2 + hstepB, voffB); PG8_STAGE(PG8_SA(0, 0), a2, vo2);
;             PG8_WAIT_V(8); PG8_WAIT_L(0); PG8_BAR; PG8_MMA(1, 0, At, B0); PG8_MMA(1, 1, At, B1); PG8_BAR; PG8_SCHED;
.LBB0_866:
	s_ashr_i32 s17, s16, 31
	s_lshl_b64 s[12:13], s[16:17], 21
	s_add_u32 s20, s82, s12
	s_addc_u32 s21, s83, s13
	s_and_b64 s[12:13], s[0:1], exec
	s_cselect_b32 s17, s21, s27
	s_cselect_b32 s48, s20, s26
	s_ashr_i32 s19, s18, 31
	s_lshl_b64 s[12:13], s[18:19], 21
	s_add_u32 s22, s78, s12
	s_addc_u32 s23, s79, s13
	s_and_b64 s[12:13], s[0:1], exec
	s_cselect_b32 s19, s23, s29
	s_cselect_b32 s49, s22, s28
	s_add_u32 s50, s28, 0x100
	s_addc_u32 s51, s29, 0
	s_mov_b32 s28, -2
	s_movk_i32 s52, 0x1000
	s_add_i32 s53, s28, 2
	s_lshr_b32 s2, s53, 2
	s_lshl_b64 s[12:13], s[2:3], 17
	s_add_i32 s2, s52, 0xfffff000
	s_and_b32 s2, s2, 0x1000
	s_add_u32 s12, s26, s12
	s_addc_u32 s13, s27, s13
	s_add_u32 s29, s12, s2
	s_addc_u32 s30, s13, 0
	s_add_i32 s2, s28, 4
	ds_read_b128 v[140:143], v151
	ds_read_b128 v[144:147], v151 offset:1024
	ds_read_b128 v[154:157], v151 offset:2048
	ds_read_b128 v[158:161], v151 offset:3072
	ds_read_b128 v[162:165], v152
	ds_read_b128 v[166:169], v152 offset:1024
	ds_read_b128 v[170:173], v152 offset:2048
	ds_read_b128 v[174:177], v152 offset:3072
	s_lshr_b32 s2, s2, 2
	s_lshl_b64 s[12:13], s[2:3], 17
	s_and_b32 s2, s52, 0x1000
	s_add_u32 s12, s26, s12
	s_addc_u32 s13, s27, s13
	s_add_u32 s2, s12, s2
	s_addc_u32 s31, s13, 0
	s_add_u32 s12, s29, 0x10800
	s_addc_u32 s13, s30, 0
	s_cmp_eq_u32 s28, 60
	s_cselect_b32 s28, s49, s50
	s_cselect_b32 s31, s17, s31
	s_cselect_b32 s30, s48, s2
	s_cselect_b32 s29, s19, s51
	s_add_i32 m0, s25, 0xc000
	ds_read_b128 v[178:181], v153
	ds_read_b128 v[182:185], v153 offset:1024
	ds_read_b128 v[186:189], v153 offset:2048
	ds_read_b128 v[190:193], v153 offset:3072
	ds_read_b128 v[194:197], v153 offset:4096
	ds_read_b128 v[198:201], v153 offset:5120
	ds_read_b128 v[202:205], v153 offset:6144
	ds_read_b128 v[206:209], v153 offset:7168
	global_load_lds_dwordx4 v134, s[12:13]
	s_add_i32 m0, s25, 0xe000
	s_nop 0
	global_load_lds_dwordx4 v130, s[12:13]
	s_waitcnt vmcnt(8)
	s_waitcnt lgkmcnt(0)
	s_barrier
	s_setprio 1
	s_waitcnt lgkmcnt(0)
	v_mfma_f32_16x16x32_bf16 v[124:127], v[140:143], v[178:181], 0
	v_mfma_f32_16x16x32_bf16 v[120:123], v[154:157], v[178:181], 0
	v_mfma_f32_16x16x32_bf16 v[108:111], v[140:143], v[186:189], 0
	v_mfma_f32_16x16x32_bf16 v[104:107], v[154:157], v[186:189], 0
	v_mfma_f32_16x16x32_bf16 v[96:99], v[140:143], v[194:197], 0
	v_mfma_f32_16x16x32_bf16 v[88:91], v[154:157], v[194:197], 0
	v_mfma_f32_16x16x32_bf16 v[80:83], v[140:143], v[202:205], 0
	v_mfma_f32_16x16x32_bf16 v[72:75], v[154:157], v[202:205], 0
	v_mfma_f32_16x16x32_bf16 v[124:127], v[144:147], v[182:185], v[124:127]
	v_mfma_f32_16x16x32_bf16 v[120:123], v[158:161], v[182:185], v[120:123]
	v_mfma_f32_16x16x32_bf16 v[108:111], v[144:147], v[190:193], v[108:111]
	v_mfma_f32_16x16x32_bf16 v[104:107], v[158:161], v[190:193], v[104:107]
	v_mfma_f32_16x16x32_bf16 v[96:99], v[144:147], v[198:201], v[96:99]
	v_mfma_f32_16x16x32_bf16 v[88:91], v[158:161], v[198:201], v[88:91]
	v_mfma_f32_16x16x32_bf16 v[80:83], v[144:147], v[206:209], v[80:83]
	v_mfma_f32_16x16x32_bf16 v[72:75], v[158:161], v[206:209], v[72:75]
	s_setprio 0
	s_setprio 1
	v_mfma_f32_16x16x32_bf16 v[116:119], v[162:165], v[178:181], 0
	v_mfma_f32_16x16x32_bf16 v[112:115], v[170:173], v[178:181], 0
	v_mfma_f32_16x16x32_bf16 v[100:103], v[162:165], v[186:189], 0
	v_mfma_f32_16x16x32_bf16 v[92:95], v[170:173], v[186:189], 0
	v_mfma_f32_16x16x32_bf16 v[84:87], v[162:165], v[194:197], 0
	v_mfma_f32_16x16x32_bf16 v[76:79], v[170:173], v[194:197], 0
	v_mfma_f32_16x16x32_bf16 v[68:71], v[162:165], v[202:205], 0
	v_mfma_f32_16x16x32_bf16 v[64:67], v[170:173], v[202:205], 0
	v_mfma_f32_16x16x32_bf16 v[116:119], v[166:169], v[182:185], v[116:119]
	v_mfma_f32_16x16x32_bf16 v[112:115], v[174:177], v[182:185], v[112:115]
	v_mfma_f32_16x16x32_bf16 v[100:103], v[166:169], v[190:193], v[100:103]
	v_mfma_f32_16x16x32_bf16 v[92:95], v[174:177], v[190:193], v[92:95]
	v_mfma_f32_16x16x32_bf16 v[84:87], v[166:169], v[198:201], v[84:87]
	v_mfma_f32_16x16x32_bf16 v[76:79], v[174:177], v[198:201], v[76:79]
	v_mfma_f32_16x16x32_bf16 v[68:71], v[166:169], v[206:209], v[68:71]
	v_mfma_f32_16x16x32_bf16 v[64:67], v[174:177], v[206:209], v[64:67]
	s_setprio 0
	s_barrier
	s_add_u32 s98, s28, s6
	s_addc_u32 s99, s29, s7
	s_add_u32 s100, s30, s8
	s_addc_u32 s101, s31, s9
	s_add_i32 s2, s44, s33
	s_mov_b32 m0, s2
	ds_read_b128 v[178:181], v153 offset:16384
	ds_read_b128 v[182:185], v153 offset:17408
	ds_read_b128 v[186:189], v153 offset:18432
	ds_read_b128 v[190:193], v153 offset:19456
	ds_read_b128 v[194:197], v153 offset:20480
	ds_read_b128 v[198:201], v153 offset:21504
	ds_read_b128 v[202:205], v153 offset:22528
	ds_read_b128 v[206:209], v153 offset:23552
	global_load_lds_dwordx4 v132, s[28:29]
	s_add_i32 m0, s2, 0x2000
	s_add_u32 s12, s28, 0x100000
	s_addc_u32 s13, s29, 0
	s_add_i32 s2, s45, s33
	global_load_lds_dwordx4 v128, s[28:29]
	s_mov_b32 m0, s2
	s_nop 0
	global_load_lds_dwordx4 v132, s[12:13]
	s_add_i32 m0, s2, 0x2000
	s_nop 0
	global_load_lds_dwordx4 v128, s[12:13]
	s_mov_b32 m0, s25
	s_nop 0
	global_load_lds_dwordx4 v134, s[30:31]
	s_mov_b32 m0, s38
	s_nop 0
	global_load_lds_dwordx4 v130, s[30:31]
	s_waitcnt vmcnt(8)
	s_waitcnt lgkmcnt(0)
	s_barrier
; #define PG8_STAGE(bufoff, gbase, voff) do { _Pragma("unroll") for (int _i = 0; _i < 2; ++_i) \
;         __builtin_amdgcn_global_load_lds((const unsigned*)((const char*)(gbase) + (voff)[_i]), (LAS unsigned*)(lds + (bufoff) + ldsw + _i * 8192), 16, 0, 0); } while (0)
; #define PG8_LDA(dst, b, h) do { _Pragma("unroll") for (int m = 0; m < 4; ++m) _Pragma("unroll") for (int k = 0; k < 2; ++k) dst[m][k] = *(const LAS bf16x8*)(lds + PG8_SA(b, h) + aoff + m * 2048 + k * 1024); } while (0)
; #define PG8_LDB(dst, b, h) do { _Pragma("unroll") for (int n = 0; n < 2; ++n) _Pragma("unroll") for (int k = 0; k < 2; ++k) dst[n][k] = *(const LAS bf16x8*)(lds + PG8_SB(b, h) + boff + n * 2048 + k * 1024); } while (0)
; #define PG8_MMA(ai, bj, At, Bt) do { __builtin_amdgcn_s_setprio(1); _Pragma("unroll") for (int m = 0; m < 4; ++m) _Pragma("unroll") for (int n = 0; n < 2; ++n) _Pragma("unroll") for (int k = 0; k < 2; ++k) \
;         acc[ai][bj][m][n] = __builtin_amdgcn_mfma_f32_16x16x32_bf16(Bt[n][k], At[m][k], acc[ai][bj][m][n], 0, 0, 0); __builtin_amdgcn_s_setprio(0); } while (0)
; #define PG8_WAIT_V(n) asm volatile("s_waitcnt vmcnt(" #n ")" ::: "memory")
; #define PG8_WAIT_L(n) asm volatile("s_waitcnt lgkmcnt(" #n ")" ::: "memory")
; #define PG8_BAR __builtin_amdgcn_s_barrier()
; #define PG8_SCHED __builtin_amdgcn_sched_barrier(0)
; template <class Epi, bool ALIGN_EPI, bool SPLITA>
; __device__ __forceinline__ void gemm_phase(LAS unsigned char* lds, const Gemm g, const StaticOrder& S, const Epi& E) {
;     ...
;             PG8_WAIT_V(8); PG8_WAIT_L(0); PG8_BAR; PG8_MMA(1, 0, At, B0); PG8_MMA(1, 1, At, B1); PG8_BAR; PG8_SCHED;
;             PG8_LDB(B0, 1, 0); PG8_LDB(B1, 1, 1); PG8_SCHED; PG8_LDA(At, 1, 0); PG8_STAGE(PG8_SA(0, 1), a2h, vo2);
;             PG8_WAIT_V(8); PG8_WAIT_L(0); PG8_BAR; PG8_MMA(0, 0, At, B0); PG8_MMA(0, 1, At, B1); PG8_BAR; PG8_SCHED;
	s_setprio 1
	s_waitcnt lgkmcnt(0)
	v_mfma_f32_16x16x32_bf16 v[60:63], v[140:143], v[178:181], 0
	v_mfma_f32_16x16x32_bf16 v[56:59], v[154:157], v[178:181], 0
	v_mfma_f32_16x16x32_bf16 v[40:43], v[140:143], v[186:189], 0
	v_mfma_f32_16x16x32_bf16 v[32:35], v[154:157], v[186:189], 0
	v_mfma_f32_16x16x32_bf16 v[20:23], v[140:143], v[194:197], 0
	v_mfma_f32_16x16x32_bf16 v[8:11], v[154:157], v[194:197], 0
	v_mfma_f32_16x16x32_bf16 v[4:7], v[140:143], v[202:205], 0
	v_mfma_f32_16x16x32_bf16 v[0:3], v[154:157], v[202:205], 0
	v_mfma_f32_16x16x32_bf16 v[60:63], v[144:147], v[182:185], v[60:63]
	v_mfma_f32_16x16x32_bf16 v[56:59], v[158:161], v[182:185], v[56:59]
	v_mfma_f32_16x16x32_bf16 v[40:43], v[144:147], v[190:193], v[40:43]
	v_mfma_f32_16x16x32_bf16 v[32:35], v[158:161], v[190:193], v[32:35]
	v_mfma_f32_16x16x32_bf16 v[20:23], v[144:147], v[198:201], v[20:23]
	v_mfma_f32_16x16x32_bf16 v[8:11], v[158:161], v[198:201], v[8:11]
	v_mfma_f32_16x16x32_bf16 v[4:7], v[144:147], v[206:209], v[4:7]
	v_mfma_f32_16x16x32_bf16 v[0:3], v[158:161], v[206:209], v[0:3]
	s_setprio 0
	s_setprio 1
	v_mfma_f32_16x16x32_bf16 v[44:47], v[162:165], v[178:181], 0
	v_mfma_f32_16x16x32_bf16 v[36:39], v[170:173], v[178:181], 0
	v_mfma_f32_16x16x32_bf16 v[52:55], v[162:165], v[186:189], 0
	v_mfma_f32_16x16x32_bf16 v[48:51], v[170:173], v[186:189], 0
	v_mfma_f32_16x16x32_bf16 v[28:31], v[162:165], v[194:197], 0
	v_mfma_f32_16x16x32_bf16 v[24:27], v[170:173], v[194:197], 0
	v_mfma_f32_16x16x32_bf16 v[16:19], v[162:165], v[202:205], 0
	v_mfma_f32_16x16x32_bf16 v[12:15], v[170:173], v[202:205], 0
	v_mfma_f32_16x16x32_bf16 v[44:47], v[166:169], v[182:185], v[44:47]
	v_mfma_f32_16x16x32_bf16 v[36:39], v[174:177], v[182:185], v[36:39]
	v_mfma_f32_16x16x32_bf16 v[52:55], v[166:169], v[190:193], v[52:55]
	v_mfma_f32_16x16x32_bf16 v[48:51], v[174:177], v[190:193], v[48:51]
	v_mfma_f32_16x16x32_bf16 v[28:31], v[166:169], v[198:201], v[28:31]
	v_mfma_f32_16x16x32_bf16 v[24:27], v[174:177], v[198:201], v[24:27]
	v_mfma_f32_16x16x32_bf16 v[16:19], v[166:169], v[206:209], v[16:19]
	v_mfma_f32_16x16x32_bf16 v[12:15], v[174:177], v[206:209], v[12:15]
	s_setprio 0
	s_barrier
	s_add_i32 s2, 0, 0x18000
	s_add_i32 s54, 0, 0x1c000
	v_add_u32_e32 v158, s2, v149
	v_add_u32_e32 v174, s54, v149
	ds_read_b128 v[140:143], v158
	ds_read_b128 v[144:147], v158 offset:1024
	ds_read_b128 v[154:157], v158 offset:2048
	ds_read_b128 v[158:161], v158 offset:3072
	ds_read_b128 v[162:165], v174
	ds_read_b128 v[166:169], v174 offset:1024
	ds_read_b128 v[170:173], v174 offset:2048
	ds_read_b128 v[174:177], v174 offset:3072
	s_add_u32 s12, s30, 0x10000
	s_addc_u32 s13, s31, 0
	s_mov_b32 m0, s39
	ds_read_b128 v[178:181], v153 offset:32768
	ds_read_b128 v[182:185], v153 offset:33792
	ds_read_b128 v[186:189], v153 offset:34816
	ds_read_b128 v[190:193], v153 offset:35840
	ds_read_b128 v[194:197], v153 offset:36864
	ds_read_b128 v[198:201], v153 offset:37888
	ds_read_b128 v[202:205], v153 offset:38912
	ds_read_b128 v[206:209], v153 offset:39936
	global_load_lds_dwordx4 v134, s[12:13]
	s_mov_b32 m0, s40
	s_nop 0
	global_load_lds_dwordx4 v130, s[12:13]
	s_waitcnt vmcnt(8)
	s_waitcnt lgkmcnt(0)
	s_barrier
	s_setprio 1
	s_waitcnt lgkmcnt(0)
	v_mfma_f32_16x16x32_bf16 v[124:127], v[140:143], v[178:181], v[124:127]
	v_mfma_f32_16x16x32_bf16 v[120:123], v[154:157], v[178:181], v[120:123]
	v_mfma_f32_16x16x32_bf16 v[108:111], v[140:143], v[186:189], v[108:111]
	v_mfma_f32_16x16x32_bf16 v[104:107], v[154:157], v[186:189], v[104:107]
	v_mfma_f32_16x16x32_bf16 v[96:99], v[140:143], v[194:197], v[96:99]
	v_mfma_f32_16x16x32_bf16 v[88:91], v[154:157], v[194:197], v[88:91]
	v_mfma_f32_16x16x32_bf16 v[80:83], v[140:143], v[202:205], v[80:83]
	v_mfma_f32_16x16x32_bf16 v[72:75], v[154:157], v[202:205], v[72:75]
	v_mfma_f32_16x16x32_bf16 v[124:127], v[144:147], v[182:185], v[124:127]
	v_mfma_f32_16x16x32_bf16 v[120:123], v[158:161], v[182:185], v[120:123]
	v_mfma_f32_16x16x32_bf16 v[108:111], v[144:147], v[190:193], v[108:111]
	v_mfma_f32_16x16x32_bf16 v[104:107], v[158:161], v[190:193], v[104:107]
	v_mfma_f32_16x16x32_bf16 v[96:99], v[144:147], v[198:201], v[96:99]
	v_mfma_f32_16x16x32_bf16 v[88:91], v[158:161], v[198:201], v[88:91]
	v_mfma_f32_16x16x32_bf16 v[80:83], v[144:147], v[206:209], v[80:83]
	v_mfma_f32_16x16x32_bf16 v[72:75], v[158:161], v[206:209], v[72:75]
	s_setprio 0
	s_setprio 1
	v_mfma_f32_16x16x32_bf16 v[116:119], v[162:165], v[178:181], v[116:119]
	v_mfma_f32_16x16x32_bf16 v[112:115], v[170:173], v[178:181], v[112:115]
	v_mfma_f32_16x16x32_bf16 v[100:103], v[162:165], v[186:189], v[100:103]
	v_mfma_f32_16x16x32_bf16 v[92:95], v[170:173], v[186:189], v[92:95]
	v_mfma_f32_16x16x32_bf16 v[84:87], v[162:165], v[194:197], v[84:87]
	v_mfma_f32_16x16x32_bf16 v[76:79], v[170:173], v[194:197], v[76:79]
	v_mfma_f32_16x16x32_bf16 v[68:71], v[162:165], v[202:205], v[68:71]
	v_mfma_f32_16x16x32_bf16 v[64:67], v[170:173], v[202:205], v[64:67]
	v_mfma_f32_16x16x32_bf16 v[116:119], v[166:169], v[182:185], v[116:119]
	v_mfma_f32_16x16x32_bf16 v[112:115], v[174:177], v[182:185], v[112:115]
	v_mfma_f32_16x16x32_bf16 v[100:103], v[166:169], v[190:193], v[100:103]
	v_mfma_f32_16x16x32_bf16 v[92:95], v[174:177], v[190:193], v[92:95]
	v_mfma_f32_16x16x32_bf16 v[84:87], v[166:169], v[198:201], v[84:87]
	v_mfma_f32_16x16x32_bf16 v[76:79], v[174:177], v[198:201], v[76:79]
	v_mfma_f32_16x16x32_bf16 v[68:71], v[166:169], v[206:209], v[68:71]
	v_mfma_f32_16x16x32_bf16 v[64:67], v[174:177], v[206:209], v[64:67]
	s_setprio 0
	s_barrier
; #define PG8_STAGE(bufoff, gbase, voff) do { _Pragma("unroll") for (int _i = 0; _i < 2; ++_i) \
;         __builtin_amdgcn_global_load_lds((const unsigned*)((const char*)(gbase) + (voff)[_i]), (LAS unsigned*)(lds + (bufoff) + ldsw + _i * 8192), 16, 0, 0); } while (0)
; #define PG8_LDA(dst, b, h) do { _Pragma("unroll") for (int m = 0; m < 4; ++m) _Pragma("unroll") for (int k = 0; k < 2; ++k) dst[m][k] = *(const LAS bf16x8*)(lds + PG8_SA(b, h) + aoff + m * 2048 + k * 1024); } while (0)
; #define PG8_MMA(ai, bj, At, Bt) do { __builtin_amdgcn_s_setprio(1); _Pragma("unroll") for (int m = 0; m < 4; ++m) _Pragma("unroll") for (int n = 0; n < 2; ++n) _Pragma("unroll") for (int k = 0; k < 2; ++k) \
;         acc[ai][bj][m][n] = __builtin_amdgcn_mfma_f32_16x16x32_bf16(Bt[n][k], At[m][k], acc[ai][bj][m][n], 0, 0, 0); __builtin_amdgcn_s_setprio(0); } while (0)
; #define PG8_WAIT_V(n) asm volatile("s_waitcnt vmcnt(" #n ")" ::: "memory")
; #define PG8_WAIT_L(n) asm volatile("s_waitcnt lgkmcnt(" #n ")" ::: "memory")
; #define PG8_BAR __builtin_amdgcn_s_barrier()
; #define PG8_SCHED __builtin_amdgcn_sched_barrier(0)
; template <class Epi, bool ALIGN_EPI, bool SPLITA>
; __device__ __forceinline__ void gemm_phase(LAS unsigned char* lds, const Gemm g, const StaticOrder& S, const Epi& E) {
;     ...
;             PG8_LDA(At, 1, 1); PG8_STAGE(PG8_SB(1, 0), b3, voffB); PG8_STAGE(PG8_SB(1, 1), b3 + hstepB, voffB); PG8_STAGE(PG8_SA(1, 0), a3, vo2);
;             PG8_WAIT_V(8); PG8_WAIT_L(0); PG8_BAR; PG8_MMA(1, 0, At, B0); PG8_MMA(1, 1, At, B1); PG8_BAR; PG8_SCHED;
	s_add_i32 s2, s2, s33
	s_mov_b32 m0, s2
	ds_read_b128 v[178:181], v153 offset:49152
	ds_read_b128 v[182:185], v153 offset:50176
	ds_read_b128 v[186:189], v153 offset:51200
	ds_read_b128 v[190:193], v153 offset:52224
	ds_read_b128 v[194:197], v153 offset:53248
	ds_read_b128 v[198:201], v153 offset:54272
	ds_read_b128 v[202:205], v153 offset:55296
	ds_read_b128 v[206:209], v153 offset:56320
	global_load_lds_dwordx4 v132, s[98:99]
	s_add_i32 m0, s2, 0x2000
	s_add_u32 s12, s28, 0x100080
	s_addc_u32 s13, s29, 0
	s_add_i32 s2, s54, s33
	global_load_lds_dwordx4 v128, s[98:99]
	s_mov_b32 m0, s2
	s_nop 0
	global_load_lds_dwordx4 v132, s[12:13]
	s_add_i32 m0, s2, 0x2000
	s_nop 0
	global_load_lds_dwordx4 v128, s[12:13]
	s_mov_b32 m0, s41
	s_nop 0
	global_load_lds_dwordx4 v134, s[100:101]
	s_mov_b32 m0, s42
	s_nop 0
	global_load_lds_dwordx4 v130, s[100:101]
	s_waitcnt vmcnt(8)
	s_waitcnt lgkmcnt(0)
	s_barrier
	s_setprio 1
	s_waitcnt lgkmcnt(0)
	v_mfma_f32_16x16x32_bf16 v[60:63], v[140:143], v[178:181], v[60:63]
	v_mfma_f32_16x16x32_bf16 v[56:59], v[154:157], v[178:181], v[56:59]
	v_mfma_f32_16x16x32_bf16 v[40:43], v[140:143], v[186:189], v[40:43]
	v_mfma_f32_16x16x32_bf16 v[32:35], v[154:157], v[186:189], v[32:35]
	v_mfma_f32_16x16x32_bf16 v[20:23], v[140:143], v[194:197], v[20:23]
	v_mfma_f32_16x16x32_bf16 v[8:11], v[154:157], v[194:197], v[8:11]
	v_mfma_f32_16x16x32_bf16 v[4:7], v[140:143], v[202:205], v[4:7]
	v_mfma_f32_16x16x32_bf16 v[0:3], v[154:157], v[202:205], v[0:3]
	v_mfma_f32_16x16x32_bf16 v[60:63], v[144:147], v[182:185], v[60:63]
	v_mfma_f32_16x16x32_bf16 v[56:59], v[158:161], v[182:185], v[56:59]
	v_mfma_f32_16x16x32_bf16 v[40:43], v[144:147], v[190:193], v[40:43]
	v_mfma_f32_16x16x32_bf16 v[32:35], v[158:161], v[190:193], v[32:35]
	v_mfma_f32_16x16x32_bf16 v[20:23], v[144:147], v[198:201], v[20:23]
	v_mfma_f32_16x16x32_bf16 v[8:11], v[158:161], v[198:201], v[8:11]
	v_mfma_f32_16x16x32_bf16 v[4:7], v[144:147], v[206:209], v[4:7]
	v_mfma_f32_16x16x32_bf16 v[0:3], v[158:161], v[206:209], v[0:3]
	s_setprio 0
	s_setprio 1
	v_mfma_f32_16x16x32_bf16 v[44:47], v[162:165], v[178:181], v[44:47]
	v_mfma_f32_16x16x32_bf16 v[36:39], v[170:173], v[178:181], v[36:39]
	v_mfma_f32_16x16x32_bf16 v[52:55], v[162:165], v[186:189], v[52:55]
	v_mfma_f32_16x16x32_bf16 v[48:51], v[170:173], v[186:189], v[48:51]
	v_mfma_f32_16x16x32_bf16 v[28:31], v[162:165], v[194:197], v[28:31]
	v_mfma_f32_16x16x32_bf16 v[24:27], v[170:173], v[194:197], v[24:27]
	v_mfma_f32_16x16x32_bf16 v[16:19], v[162:165], v[202:205], v[16:19]
	v_mfma_f32_16x16x32_bf16 v[12:15], v[170:173], v[202:205], v[12:15]
	v_mfma_f32_16x16x32_bf16 v[44:47], v[166:169], v[182:185], v[44:47]
	v_mfma_f32_16x16x32_bf16 v[36:39], v[174:177], v[182:185], v[36:39]
	v_mfma_f32_16x16x32_bf16 v[52:55], v[166:169], v[190:193], v[52:55]
	v_mfma_f32_16x16x32_bf16 v[48:51], v[174:177], v[190:193], v[48:51]
	v_mfma_f32_16x16x32_bf16 v[28:31], v[166:169], v[198:201], v[28:31]
	v_mfma_f32_16x16x32_bf16 v[24:27], v[174:177], v[198:201], v[24:27]
	v_mfma_f32_16x16x32_bf16 v[16:19], v[166:169], v[206:209], v[16:19]
	v_mfma_f32_16x16x32_bf16 v[12:15], v[174:177], v[206:209], v[12:15]
	s_setprio 0
	s_barrier
	s_add_u32 s50, s50, 0x100
	s_addc_u32 s51, s51, 0
	s_addk_i32 s52, 0x1000
	s_mov_b32 s28, s53
